# v53 + static priority: trailing half s_setprio 1 once per GEMM phase, all per-segment s_setprio flips removed from the 5 K-loops
# speedup vs baseline: 1.0116x; 1.0037x over previous
; __device__ __forceinline__ unsigned xb_ld(unsigned* p)              { return __hip_atomic_load(p, __ATOMIC_RELAXED, __HIP_MEMORY_SCOPE_AGENT); }
; __device__ __forceinline__ void xcd_barrier_complete(unsigned* bar, unsigned x, unsigned& nloc, unsigned& nx) {
;     const unsigned G = gridDim.x * gridDim.y * gridDim.z;
;     unsigned sum, cnt, mine, sp = 0u;
;     for (;;) {
;         sum = 0u; cnt = 0u; mine = 0u;
; #pragma unroll
;         for (unsigned j = 0; j < 16; ++j) { const unsigned c = xb_ld(&bar[XB_XCNT(j)]); sum += c; cnt += (c > 0u) ? 1u : 0u; mine = (j == x) ? c : mine; }
; __device__ __forceinline__ void xcd_barrier(const XcdBarrier& b) {
;     asm volatile("s_waitcnt vmcnt(0)" ::: "memory");
;     __syncthreads();
;     if (threadIdx.x == 0) {
;         unsigned* bar = b.bar;
;         __builtin_amdgcn_s_waitcnt(0);
;         unsigned nloc = b.st[0], nx = b.st[1];
;         if (nloc == 0u) { xcd_barrier_complete(bar, b.x, nloc, nx); b.st[0] = nloc; b.st[1] = nx; }
.LBB0_67:
	v_readlane_b32 s8, v253, 2
	v_readlane_b32 s11, v253, 5
	s_cmp_gt_u32 s11, 1
	s_cselect_b64 s[0:1], -1, 0
	s_and_b64 s[0:1], s[12:13], s[0:1]
	s_andn2_b64 vcc, exec, s[0:1]
	v_readlane_b32 s9, v253, 3
	v_readlane_b32 s10, v253, 4
	s_cbranch_vccnz .LBB0_121
	s_waitcnt vmcnt(0)
	s_waitcnt lgkmcnt(0)
	s_barrier
	s_setprio 0
	s_and_saveexec_b64 s[0:1], s[80:81]
	s_cbranch_execz .LBB0_120
	s_add_i32 s3, 0, 0x26160
	v_mov_b32_e32 v1, s3
	s_waitcnt vmcnt(0) expcnt(0) lgkmcnt(0)
	ds_read_b32 v3, v1
	s_add_i32 s3, 0, 0x26164
	v_mov_b32_e32 v1, s3
	ds_read_b32 v1, v1
	s_waitcnt lgkmcnt(1)
	v_cmp_ne_u32_e32 vcc, 0, v3
	s_cbranch_vccnz .LBB0_84
	v_readlane_b32 s6, v253, 0
	v_readlane_b32 s7, v253, 1
	s_load_dwordx2 s[10:11], s[6:7], 0x88
	s_load_dword s3, s[6:7], 0x90
	v_readlane_b32 s40, v253, 2
	v_readlane_b32 s41, v253, 3
	s_add_u32 s6, s40, 0x4200
	s_addc_u32 s7, s41, 0
	s_add_u32 s8, s40, 0x4400
	s_waitcnt lgkmcnt(0)
	s_mul_i32 s9, s11, s10
	s_mul_i32 s3, s9, s3
	s_addc_u32 s9, s41, 0
	s_add_u32 s10, s40, 0x4500
	s_addc_u32 s11, s41, 0
	s_add_u32 s12, s40, 0x4600
	s_addc_u32 s13, s41, 0
	s_add_u32 s14, s40, 0x4700
	s_addc_u32 s15, s41, 0
	s_add_u32 s16, s40, 0x4800
	s_addc_u32 s17, s41, 0
	s_add_u32 s18, s40, 0x4900
	s_addc_u32 s19, s41, 0
	s_add_u32 s20, s40, 0x4a00
	s_addc_u32 s21, s41, 0
	s_add_u32 s22, s40, 0x4b00
	s_addc_u32 s23, s41, 0
	s_add_u32 s24, s40, 0x4c00
	s_addc_u32 s25, s41, 0
	s_add_u32 s26, s40, 0x4d00
	s_addc_u32 s27, s41, 0
	s_add_u32 s28, s40, 0x4e00
	s_addc_u32 s29, s41, 0
	s_add_u32 s30, s40, 0x4f00
	s_addc_u32 s31, s41, 0
	s_add_u32 s34, s40, 0x5000
	s_addc_u32 s35, s41, 0
	s_add_u32 s36, s40, 0x5100
	s_addc_u32 s37, s41, 0
	s_add_u32 s38, s40, 0x5200
	s_addc_u32 s39, s41, 0
	s_add_u32 s40, s40, 0x5300
	s_addc_u32 s41, s41, 0
	s_mov_b32 s48, 1
	v_mov_b32_e32 v17, 0
	v_readlane_b32 s42, v253, 4
	v_readlane_b32 s43, v253, 5
	s_branch .LBB0_72

; #define PG8_STAGE(bufoff, gbase, voff) do { _Pragma("unroll") for (int _i = 0; _i < 2; ++_i) \
;         __builtin_amdgcn_global_load_lds((const unsigned*)((const char*)(gbase) + (voff)[_i]), (PG8_LAS unsigned*)(lds + (bufoff) + ldsw + _i * 8192), 16, 0, 0); } while (0)
; #define PG8_WAIT_V(n) asm volatile("s_waitcnt vmcnt(" #n ")" ::: "memory")
; #define PG8_BAR __builtin_amdgcn_s_barrier()
; template <class Epi, class Sched, bool ALIGN_EPI = false, bool SP2 = false>
; __device__ __forceinline__ void gemm_phase(PG8_LAS unsigned char* lds, const Gemm g, const Sched& S, const Epi& E) {
;     ...
;     for (int i = 0; i < 2; ++i) { int R, C; stage_rc(tid * 16 + i * 8192, R, C); const int Rb = Epi::PERM ? ((R & ~31) + perm32(R & 31)) : R;
;         voffA[i] = (unsigned)(R * K + C) * 2u; voffB[i] = (unsigned)(Rb * K + C) * 2u; }
;     const size_t kstep = (size_t)(BK * 2);
;     const size_t hstep = (size_t)HALF * K * 2;
;     const size_t tstep = 2 * hstep;
;     const unsigned ldsw = (unsigned)wid * 1024u;
;     const int aoff = lds_byte(wr * 64 + fr, fq * 8), boff = lds_byte(wc * 32 + fr, fq * 8);
;     ...
;         PG8_WAIT_V(2); PG8_BAR;
;         PG8_STAGE(PG8_SB(1, 0), cB + kstep, voffB); PG8_STAGE(PG8_SA(1, 0), cA + kstep, voffA); PG8_STAGE(PG8_SB(1, 1), cB + hstep + kstep, voffB);
;         PG8_WAIT_V(6); PG8_BAR;
.LBB0_133:
	s_lshl_b32 s1, s1, 5
	s_and_b32 s1, s1, 0x60
	s_add_i32 m0, s53, 0x18000
	v_lshl_add_u64 v[8:9], v[8:9], 0, s[10:11]
	s_lshl_b32 s17, s0, 13
	s_lshl_b32 s24, s1, 7
	s_waitcnt vmcnt(2)
	s_barrier
	global_load_lds_dwordx4 v[8:9], off
	v_lshl_add_u64 v[6:7], v[6:7], 0, s[10:11]
	s_add_i32 m0, s53, 0x1a000
	s_add_i32 s57, s53, 0x8000
	s_add_i32 s58, s53, 0xa000
	global_load_lds_dwordx4 v[6:7], off
	v_lshl_add_u64 v[2:3], v[2:3], 0, s[10:11]
	s_mov_b32 m0, s57
	s_add_u32 s22, s36, 0x80080
	global_load_lds_dwordx4 v[2:3], off
	v_lshl_add_u64 v[2:3], v[4:5], 0, s[10:11]
	s_mov_b32 m0, s58
	s_addc_u32 s23, s37, 0
	global_load_lds_dwordx4 v[2:3], off
	s_add_i32 m0, s53, 0x1c000
	v_lshl_add_u64 v[2:3], s[22:23], 0, v[158:159]
	global_load_lds_dwordx4 v[2:3], off
	v_lshl_add_u64 v[2:3], s[22:23], 0, v[134:135]
	s_add_i32 m0, s53, 0x1e000
	s_cmpk_lt_u32 s16, 0x100
	global_load_lds_dwordx4 v[2:3], off
	v_and_b32_e32 v3, 15, v146
	v_and_b32_e32 v2, 48, v146
	v_lshl_or_b32 v147, s0, 6, v3
	v_lshl_or_b32 v4, v3, 6, v2
	v_lshlrev_b32_e32 v3, 2, v3
	v_and_b32_e32 v5, 32, v3
	v_bitop3_b32 v6, v4, s17, v5 bitop3:0xde
	s_cselect_b64 s[16:17], -1, 0
	s_cbranch_scc1 .Lsp_1
	s_setprio 1
.Lsp_1:
	s_lshl_b32 s0, s0, 8
	s_add_i32 s22, 0, 0x20000
	s_add_i32 s0, s22, s0
	s_ashr_i32 s59, s48, 31
	v_add_u32_e32 v149, s0, v3
	s_lshl_b32 s0, s1, 1
	s_add_u32 s0, s4, s0
	s_addc_u32 s1, s5, 0
	v_mov_b32_e32 v3, v159
	v_lshl_add_u64 v[2:3], s[0:1], 0, v[2:3]
	s_mov_b64 s[0:1], 0x25800000
	v_lshl_add_u64 v[136:137], v[2:3], 0, s[0:1]
	v_lshlrev_b32_e32 v2, 15, v10
	v_and_b32_e32 v2, 0xffff0000, v2
	v_lshl_add_u32 v2, v11, 12, v2
	v_and_b32_e32 v3, 1, v10
	v_lshl_or_b32 v2, v3, 6, v2
	v_lshl_add_u32 v138, v12, 1, v2
	v_lshlrev_b32_e32 v2, 15, v13
	v_and_b32_e32 v2, 0xffff0000, v2
	s_waitcnt vmcnt(6)
	v_lshl_add_u32 v2, v14, 12, v2
	v_and_b32_e32 v3, 1, v13
	v_lshl_or_b32 v2, v3, 6, v2
	v_readlane_b32 s0, v252, 18
	v_bitop3_b32 v148, v4, s24, v5 bitop3:0xde
	v_lshl_add_u32 v150, v146, 2, s22
	v_mov_b32_e32 v139, v159
	v_lshl_add_u32 v140, v15, 1, v2
	v_mov_b32_e32 v141, v159
	s_mov_b32 s60, 0
	v_add_u32_e32 v151, 0, v6
	v_readlane_b32 s63, v254, 49
	s_mov_b32 s44, s0
	s_mov_b32 s62, s0
	s_mov_b32 s61, 0
	s_barrier
	v_readlane_b32 s1, v252, 19
	s_branch .LBB0_136

; #define PG8_STAGE(bufoff, gbase, voff) do { _Pragma("unroll") for (int _i = 0; _i < 2; ++_i) \
;         __builtin_amdgcn_global_load_lds((const unsigned*)((const char*)(gbase) + (voff)[_i]), (PG8_LAS unsigned*)(lds + (bufoff) + ldsw + _i * 8192), 16, 0, 0); } while (0)
; #define PG8_LDA(dst, b, h) do { _Pragma("unroll") for (int m = 0; m < 4; ++m) _Pragma("unroll") for (int k = 0; k < 2; ++k) dst[m][k] = *(const PG8_LAS bf16x8*)(lds + PG8_SA(b, h) + aoff + m * 2048 + k * 1024); } while (0)
; #define PG8_LDB(dst, b, h) do { _Pragma("unroll") for (int n = 0; n < 2; ++n) _Pragma("unroll") for (int k = 0; k < 2; ++k) dst[n][k] = *(const PG8_LAS bf16x8*)(lds + PG8_SB(b, h) + boff + n * 2048 + k * 1024); } while (0)
; #define PG8_MMA(ai, bj, At, Bt) do { __builtin_amdgcn_s_setprio(1); _Pragma("unroll") for (int m = 0; m < 4; ++m) _Pragma("unroll") for (int n = 0; n < 2; ++n) _Pragma("unroll") for (int k = 0; k < 2; ++k) \
;         acc[ai][bj][m][n] = __builtin_amdgcn_mfma_f32_16x16x32_bf16(Bt[n][k], At[m][k], acc[ai][bj][m][n], 0, 0, 0); __builtin_amdgcn_s_setprio(0); } while (0)
; #define PG8_WAIT_V(n) asm volatile("s_waitcnt vmcnt(" #n ")" ::: "memory")
; #define PG8_BAR __builtin_amdgcn_s_barrier()
; template <class Epi, class Sched, bool ALIGN_EPI = false, bool SP2 = false>
; __device__ __forceinline__ void gemm_phase(PG8_LAS unsigned char* lds, const Gemm g, const Sched& S, const Epi& E) {
;     ...
;         for (int t = 0; t < nt; t += 2) {
;             const bool last = (t == nt - 2);
;             const char* a1 = cA + (size_t)(t + 1) * kstep;
;             const char* a2 = last ? nA : cA + (size_t)(t + 2) * kstep; const char* b2 = last ? nB : cB + (size_t)(t + 2) * kstep;
;             const char* a3 = a2 + kstep; const char* b3 = b2 + kstep;
;             if (last && has_next) S.a_ready(nxt);
;             if constexpr (SP2) {
;             PG8_LDB(B0, 0, 0); PG8_LDB(B1, 0, 1); PG8_SCHED; PG8_LDA(At, 0, 0); PG8_STAGE(PG8_SA(1, 1), a1 + hstep, voffA);
;             PG8_WAIT_V(8); PG8_WAIT_L(0); PG8_BAR; PG8_MMA(0, 0, At, B0); PG8_MMA(0, 1, At, B1); PG8_BAR; PG8_SCHED;
;             PG8_LDA(At, 0, 1); PG8_STAGE(PG8_SB(0, 0), b2, voffB); PG8_STAGE(PG8_SB(0, 1), b2 + hstep, voffB); PG8_STAGE(PG8_SA(0, 0), a2, voffA);
;             PG8_WAIT_V(8); PG8_WAIT_L(0); PG8_BAR; PG8_MMA(1, 0, At, B0); PG8_MMA(1, 1, At, B1); PG8_BAR; PG8_SCHED;
.LBB0_139:
	s_add_u32 s36, s30, 0xfff80080
	s_addc_u32 s37, s31, -1
	s_add_i32 s70, 0, 0x10000
	s_cmp_eq_u32 s69, 28
	s_cselect_b32 s39, s25, s37
	s_cselect_b32 s38, s45, s36
	v_add_u32_e32 v142, s70, v148
	s_cselect_b32 s37, s23, s68
	s_cselect_b32 s36, s66, s67
	s_add_i32 s75, 0, 0x14000
	ds_read_b128 v[152:155], v142
	ds_read_b128 v[166:169], v142 offset:1024
	ds_read_b128 v[170:173], v142 offset:2048
	ds_read_b128 v[174:177], v142 offset:3072
	v_add_u32_e32 v142, s75, v148
	ds_read_b128 v[178:181], v142
	ds_read_b128 v[182:185], v142 offset:1024
	ds_read_b128 v[186:189], v142 offset:2048
	ds_read_b128 v[190:193], v142 offset:3072
	s_add_u32 s98, s30, 0xfff80000
	s_addc_u32 s99, s31, -1
	s_mov_b32 m0, s57
	s_nop 0
	global_load_lds_dwordx4 v138, s[98:99]
	s_mov_b32 m0, s58
	s_nop 0
	global_load_lds_dwordx4 v140, s[98:99]
	s_add_i32 m0, s53, 0xc000
	ds_read_b128 v[200:203], v151
	ds_read_b128 v[204:207], v151 offset:1024
	ds_read_b128 v[208:211], v151 offset:2048
	ds_read_b128 v[212:215], v151 offset:3072
	ds_read_b128 v[216:219], v151 offset:4096
	ds_read_b128 v[220:223], v151 offset:5120
	ds_read_b128 v[224:227], v151 offset:6144
	ds_read_b128 v[228:231], v151 offset:7168
	global_load_lds_dwordx4 v138, s[30:31]
	s_add_i32 m0, s53, 0xe000
	s_nop 0
	global_load_lds_dwordx4 v140, s[30:31]
	s_waitcnt vmcnt(8)
	s_waitcnt lgkmcnt(0)
	s_barrier
	s_waitcnt lgkmcnt(0)
	v_mfma_f32_16x16x32_bf16 v[126:129], v[152:155], v[200:203], v[126:129]
	v_mfma_f32_16x16x32_bf16 v[122:125], v[170:173], v[200:203], v[122:125]
	v_mfma_f32_16x16x32_bf16 v[110:113], v[152:155], v[208:211], v[110:113]
	v_mfma_f32_16x16x32_bf16 v[106:109], v[170:173], v[208:211], v[106:109]
	v_mfma_f32_16x16x32_bf16 v[94:97], v[152:155], v[216:219], v[94:97]
	v_mfma_f32_16x16x32_bf16 v[90:93], v[170:173], v[216:219], v[90:93]
	v_mfma_f32_16x16x32_bf16 v[78:81], v[152:155], v[224:227], v[78:81]
	v_mfma_f32_16x16x32_bf16 v[74:77], v[170:173], v[224:227], v[74:77]
	v_mfma_f32_16x16x32_bf16 v[126:129], v[166:169], v[204:207], v[126:129]
	v_mfma_f32_16x16x32_bf16 v[122:125], v[174:177], v[204:207], v[122:125]
	v_mfma_f32_16x16x32_bf16 v[110:113], v[166:169], v[212:215], v[110:113]
	v_mfma_f32_16x16x32_bf16 v[106:109], v[174:177], v[212:215], v[106:109]
	v_mfma_f32_16x16x32_bf16 v[94:97], v[166:169], v[220:223], v[94:97]
	v_mfma_f32_16x16x32_bf16 v[90:93], v[174:177], v[220:223], v[90:93]
	v_mfma_f32_16x16x32_bf16 v[78:81], v[166:169], v[228:231], v[78:81]
	v_mfma_f32_16x16x32_bf16 v[74:77], v[174:177], v[228:231], v[74:77]
	v_mfma_f32_16x16x32_bf16 v[118:121], v[178:181], v[200:203], v[118:121]
	v_mfma_f32_16x16x32_bf16 v[114:117], v[186:189], v[200:203], v[114:117]
	v_mfma_f32_16x16x32_bf16 v[102:105], v[178:181], v[208:211], v[102:105]
	v_mfma_f32_16x16x32_bf16 v[98:101], v[186:189], v[208:211], v[98:101]
	v_mfma_f32_16x16x32_bf16 v[86:89], v[178:181], v[216:219], v[86:89]
	v_mfma_f32_16x16x32_bf16 v[82:85], v[186:189], v[216:219], v[82:85]
	v_mfma_f32_16x16x32_bf16 v[70:73], v[178:181], v[224:227], v[70:73]
	v_mfma_f32_16x16x32_bf16 v[66:69], v[186:189], v[224:227], v[66:69]
	v_mfma_f32_16x16x32_bf16 v[118:121], v[182:185], v[204:207], v[118:121]
	v_mfma_f32_16x16x32_bf16 v[114:117], v[190:193], v[204:207], v[114:117]
	v_mfma_f32_16x16x32_bf16 v[102:105], v[182:185], v[212:215], v[102:105]
	v_mfma_f32_16x16x32_bf16 v[98:101], v[190:193], v[212:215], v[98:101]
	v_mfma_f32_16x16x32_bf16 v[86:89], v[182:185], v[220:223], v[86:89]
	v_mfma_f32_16x16x32_bf16 v[82:85], v[190:193], v[220:223], v[82:85]
	v_mfma_f32_16x16x32_bf16 v[70:73], v[182:185], v[228:231], v[70:73]
	v_mfma_f32_16x16x32_bf16 v[66:69], v[190:193], v[228:231], v[66:69]
	s_barrier
	s_add_i32 s70, s70, s52
	s_mov_b32 m0, s70
	ds_read_b128 v[200:203], v151 offset:16384
	ds_read_b128 v[204:207], v151 offset:17408
	ds_read_b128 v[208:211], v151 offset:18432
	ds_read_b128 v[212:215], v151 offset:19456
	ds_read_b128 v[216:219], v151 offset:20480
	ds_read_b128 v[220:223], v151 offset:21504
	ds_read_b128 v[224:227], v151 offset:22528
	ds_read_b128 v[228:231], v151 offset:23552
	global_load_lds_dwordx4 v158, s[36:37]
	s_add_i32 m0, s70, 0x2000
	s_add_u32 s70, s36, 0x80000
	s_addc_u32 s71, s37, 0
	s_add_i32 s75, s75, s52
	global_load_lds_dwordx4 v134, s[36:37]
	s_mov_b32 m0, s75
	s_nop 0
	global_load_lds_dwordx4 v158, s[70:71]
	s_add_i32 m0, s75, 0x2000
	s_nop 0
	global_load_lds_dwordx4 v134, s[70:71]
	s_waitcnt vmcnt(6)
	s_waitcnt lgkmcnt(0)
	s_barrier
	s_waitcnt lgkmcnt(0)
	v_mfma_f32_16x16x32_bf16 v[62:65], v[152:155], v[200:203], v[62:65]
	v_mfma_f32_16x16x32_bf16 v[58:61], v[170:173], v[200:203], v[58:61]
	v_mfma_f32_16x16x32_bf16 v[46:49], v[152:155], v[208:211], v[46:49]
	v_mfma_f32_16x16x32_bf16 v[42:45], v[170:173], v[208:211], v[42:45]
	v_mfma_f32_16x16x32_bf16 v[30:33], v[152:155], v[216:219], v[30:33]
	v_mfma_f32_16x16x32_bf16 v[26:29], v[170:173], v[216:219], v[26:29]
	v_mfma_f32_16x16x32_bf16 v[14:17], v[152:155], v[224:227], v[14:17]
	v_mfma_f32_16x16x32_bf16 v[10:13], v[170:173], v[224:227], v[10:13]
	v_mfma_f32_16x16x32_bf16 v[62:65], v[166:169], v[204:207], v[62:65]
	v_mfma_f32_16x16x32_bf16 v[58:61], v[174:177], v[204:207], v[58:61]
	v_mfma_f32_16x16x32_bf16 v[46:49], v[166:169], v[212:215], v[46:49]
	v_mfma_f32_16x16x32_bf16 v[42:45], v[174:177], v[212:215], v[42:45]
	v_mfma_f32_16x16x32_bf16 v[30:33], v[166:169], v[220:223], v[30:33]
	v_mfma_f32_16x16x32_bf16 v[26:29], v[174:177], v[220:223], v[26:29]
	v_mfma_f32_16x16x32_bf16 v[14:17], v[166:169], v[228:231], v[14:17]
	v_mfma_f32_16x16x32_bf16 v[10:13], v[174:177], v[228:231], v[10:13]
	v_mfma_f32_16x16x32_bf16 v[54:57], v[178:181], v[200:203], v[54:57]
	v_mfma_f32_16x16x32_bf16 v[50:53], v[186:189], v[200:203], v[50:53]
	v_mfma_f32_16x16x32_bf16 v[38:41], v[178:181], v[208:211], v[38:41]
	v_mfma_f32_16x16x32_bf16 v[34:37], v[186:189], v[208:211], v[34:37]
	v_mfma_f32_16x16x32_bf16 v[22:25], v[178:181], v[216:219], v[22:25]
	v_mfma_f32_16x16x32_bf16 v[18:21], v[186:189], v[216:219], v[18:21]
	v_mfma_f32_16x16x32_bf16 v[6:9], v[178:181], v[224:227], v[6:9]
	v_mfma_f32_16x16x32_bf16 v[2:5], v[186:189], v[224:227], v[2:5]
	v_mfma_f32_16x16x32_bf16 v[54:57], v[182:185], v[204:207], v[54:57]
	v_mfma_f32_16x16x32_bf16 v[50:53], v[190:193], v[204:207], v[50:53]
	v_mfma_f32_16x16x32_bf16 v[38:41], v[182:185], v[212:215], v[38:41]
	v_mfma_f32_16x16x32_bf16 v[34:37], v[190:193], v[212:215], v[34:37]
	v_mfma_f32_16x16x32_bf16 v[22:25], v[182:185], v[220:223], v[22:25]
	v_mfma_f32_16x16x32_bf16 v[18:21], v[190:193], v[220:223], v[18:21]
	v_mfma_f32_16x16x32_bf16 v[6:9], v[182:185], v[228:231], v[6:9]
	v_mfma_f32_16x16x32_bf16 v[2:5], v[190:193], v[228:231], v[2:5]
	s_barrier
; #define PG8_STAGE(bufoff, gbase, voff) do { _Pragma("unroll") for (int _i = 0; _i < 2; ++_i) \
;         __builtin_amdgcn_global_load_lds((const unsigned*)((const char*)(gbase) + (voff)[_i]), (PG8_LAS unsigned*)(lds + (bufoff) + ldsw + _i * 8192), 16, 0, 0); } while (0)
; #define PG8_LDA(dst, b, h) do { _Pragma("unroll") for (int m = 0; m < 4; ++m) _Pragma("unroll") for (int k = 0; k < 2; ++k) dst[m][k] = *(const PG8_LAS bf16x8*)(lds + PG8_SA(b, h) + aoff + m * 2048 + k * 1024); } while (0)
; #define PG8_LDB(dst, b, h) do { _Pragma("unroll") for (int n = 0; n < 2; ++n) _Pragma("unroll") for (int k = 0; k < 2; ++k) dst[n][k] = *(const PG8_LAS bf16x8*)(lds + PG8_SB(b, h) + boff + n * 2048 + k * 1024); } while (0)
; #define PG8_MMA(ai, bj, At, Bt) do { __builtin_amdgcn_s_setprio(1); _Pragma("unroll") for (int m = 0; m < 4; ++m) _Pragma("unroll") for (int n = 0; n < 2; ++n) _Pragma("unroll") for (int k = 0; k < 2; ++k) \
;         acc[ai][bj][m][n] = __builtin_amdgcn_mfma_f32_16x16x32_bf16(Bt[n][k], At[m][k], acc[ai][bj][m][n], 0, 0, 0); __builtin_amdgcn_s_setprio(0); } while (0)
; #define PG8_WAIT_V(n) asm volatile("s_waitcnt vmcnt(" #n ")" ::: "memory")
; #define PG8_WAIT_L(n) asm volatile("s_waitcnt lgkmcnt(" #n ")" ::: "memory")
; #define PG8_BAR __builtin_amdgcn_s_barrier()
; #define PG8_SCHED __builtin_amdgcn_sched_barrier(0)
; template <class Epi, class Sched, bool ALIGN_EPI = false, bool SP2 = false>
; __device__ __forceinline__ void gemm_phase(PG8_LAS unsigned char* lds, const Gemm g, const Sched& S, const Epi& E) {
;     ...
;             PG8_LDB(B0, 1, 0); PG8_LDB(B1, 1, 1); PG8_SCHED; PG8_LDA(At, 1, 0); PG8_STAGE(PG8_SA(0, 1), a2 + hstep, voffA);
;             PG8_WAIT_V(8); PG8_WAIT_L(0); PG8_BAR; PG8_MMA(0, 0, At, B0); PG8_MMA(0, 1, At, B1); PG8_BAR; PG8_SCHED;
;             PG8_LDA(At, 1, 1); PG8_STAGE(PG8_SB(1, 0), b3, voffB); PG8_STAGE(PG8_SB(1, 1), b3 + hstep, voffB); PG8_STAGE(PG8_SA(1, 0), a3, voffA);
;             PG8_WAIT_V(8); PG8_WAIT_L(0); PG8_BAR; PG8_MMA(1, 0, At, B0); PG8_MMA(1, 1, At, B1); PG8_BAR; PG8_SCHED;
;     ...
;         if constexpr (ALIGN_EPI) { if (wr == 0) PG8_BAR; }
	s_add_i32 s70, 0, 0x18000
	v_add_u32_e32 v142, s70, v148
	s_add_i32 s71, 0, 0x1c000
	ds_read_b128 v[152:155], v142
	ds_read_b128 v[166:169], v142 offset:1024
	ds_read_b128 v[170:173], v142 offset:2048
	ds_read_b128 v[174:177], v142 offset:3072
	v_add_u32_e32 v142, s71, v148
	ds_read_b128 v[178:181], v142
	ds_read_b128 v[182:185], v142 offset:1024
	ds_read_b128 v[186:189], v142 offset:2048
	ds_read_b128 v[190:193], v142 offset:3072
	s_mov_b32 m0, s53
	s_nop 0
	global_load_lds_dwordx4 v130, s[38:39]
	s_mov_b32 m0, s54
	s_nop 0
	global_load_lds_dwordx4 v132, s[38:39]
	s_add_u32 s38, s38, 0x80000
	s_addc_u32 s39, s39, 0
	s_mov_b32 m0, s55
	ds_read_b128 v[200:203], v151 offset:32768
	ds_read_b128 v[204:207], v151 offset:33792
	ds_read_b128 v[208:211], v151 offset:34816
	ds_read_b128 v[212:215], v151 offset:35840
	ds_read_b128 v[216:219], v151 offset:36864
	ds_read_b128 v[220:223], v151 offset:37888
	ds_read_b128 v[224:227], v151 offset:38912
	ds_read_b128 v[228:231], v151 offset:39936
	global_load_lds_dwordx4 v130, s[38:39]
	s_mov_b32 m0, s56
	s_nop 0
	global_load_lds_dwordx4 v132, s[38:39]
	s_waitcnt vmcnt(8)
	s_waitcnt lgkmcnt(0)
	s_barrier
	s_waitcnt lgkmcnt(0)
	v_mfma_f32_16x16x32_bf16 v[126:129], v[152:155], v[200:203], v[126:129]
	v_mfma_f32_16x16x32_bf16 v[122:125], v[170:173], v[200:203], v[122:125]
	v_mfma_f32_16x16x32_bf16 v[110:113], v[152:155], v[208:211], v[110:113]
	v_mfma_f32_16x16x32_bf16 v[106:109], v[170:173], v[208:211], v[106:109]
	v_mfma_f32_16x16x32_bf16 v[94:97], v[152:155], v[216:219], v[94:97]
	v_mfma_f32_16x16x32_bf16 v[90:93], v[170:173], v[216:219], v[90:93]
	v_mfma_f32_16x16x32_bf16 v[78:81], v[152:155], v[224:227], v[78:81]
	v_mfma_f32_16x16x32_bf16 v[74:77], v[170:173], v[224:227], v[74:77]
	v_mfma_f32_16x16x32_bf16 v[126:129], v[166:169], v[204:207], v[126:129]
	v_mfma_f32_16x16x32_bf16 v[122:125], v[174:177], v[204:207], v[122:125]
	v_mfma_f32_16x16x32_bf16 v[110:113], v[166:169], v[212:215], v[110:113]
	v_mfma_f32_16x16x32_bf16 v[106:109], v[174:177], v[212:215], v[106:109]
	v_mfma_f32_16x16x32_bf16 v[94:97], v[166:169], v[220:223], v[94:97]
	v_mfma_f32_16x16x32_bf16 v[90:93], v[174:177], v[220:223], v[90:93]
	v_mfma_f32_16x16x32_bf16 v[78:81], v[166:169], v[228:231], v[78:81]
	v_mfma_f32_16x16x32_bf16 v[74:77], v[174:177], v[228:231], v[74:77]
	v_mfma_f32_16x16x32_bf16 v[118:121], v[178:181], v[200:203], v[118:121]
	v_mfma_f32_16x16x32_bf16 v[114:117], v[186:189], v[200:203], v[114:117]
	v_mfma_f32_16x16x32_bf16 v[102:105], v[178:181], v[208:211], v[102:105]
	v_mfma_f32_16x16x32_bf16 v[98:101], v[186:189], v[208:211], v[98:101]
	v_mfma_f32_16x16x32_bf16 v[86:89], v[178:181], v[216:219], v[86:89]
	v_mfma_f32_16x16x32_bf16 v[82:85], v[186:189], v[216:219], v[82:85]
	v_mfma_f32_16x16x32_bf16 v[70:73], v[178:181], v[224:227], v[70:73]
	v_mfma_f32_16x16x32_bf16 v[66:69], v[186:189], v[224:227], v[66:69]
	v_mfma_f32_16x16x32_bf16 v[118:121], v[182:185], v[204:207], v[118:121]
	v_mfma_f32_16x16x32_bf16 v[114:117], v[190:193], v[204:207], v[114:117]
	v_mfma_f32_16x16x32_bf16 v[102:105], v[182:185], v[212:215], v[102:105]
	v_mfma_f32_16x16x32_bf16 v[98:101], v[190:193], v[212:215], v[98:101]
	v_mfma_f32_16x16x32_bf16 v[86:89], v[182:185], v[220:223], v[86:89]
	v_mfma_f32_16x16x32_bf16 v[82:85], v[190:193], v[220:223], v[82:85]
	v_mfma_f32_16x16x32_bf16 v[70:73], v[182:185], v[228:231], v[70:73]
	v_mfma_f32_16x16x32_bf16 v[66:69], v[190:193], v[228:231], v[66:69]
	s_barrier
	s_add_i32 s38, s70, s52
	s_add_i32 m0, s38, 0xffffff80
	ds_read_b128 v[200:203], v151 offset:49152
	ds_read_b128 v[204:207], v151 offset:50176
	ds_read_b128 v[208:211], v151 offset:51200
	ds_read_b128 v[212:215], v151 offset:52224
	ds_read_b128 v[216:219], v151 offset:53248
	ds_read_b128 v[220:223], v151 offset:54272
	ds_read_b128 v[224:227], v151 offset:55296
	ds_read_b128 v[228:231], v151 offset:56320
	global_load_lds_dwordx4 v158, s[36:37] offset:128
	s_add_i32 m0, s38, 0x1f80
	s_add_i32 s38, s71, s52
	global_load_lds_dwordx4 v134, s[36:37] offset:128
	s_add_u32 s36, s36, 0x80080
	s_addc_u32 s37, s37, 0
	s_mov_b32 m0, s38
	s_nop 0
	global_load_lds_dwordx4 v158, s[36:37]
	s_add_i32 m0, s38, 0x2000
	s_nop 0
	global_load_lds_dwordx4 v134, s[36:37]
	s_waitcnt vmcnt(6)
	s_waitcnt lgkmcnt(0)
	s_barrier
	s_waitcnt lgkmcnt(0)
	v_mfma_f32_16x16x32_bf16 v[62:65], v[152:155], v[200:203], v[62:65]
	v_mfma_f32_16x16x32_bf16 v[58:61], v[170:173], v[200:203], v[58:61]
	v_mfma_f32_16x16x32_bf16 v[46:49], v[152:155], v[208:211], v[46:49]
	v_mfma_f32_16x16x32_bf16 v[42:45], v[170:173], v[208:211], v[42:45]
	v_mfma_f32_16x16x32_bf16 v[30:33], v[152:155], v[216:219], v[30:33]
	v_mfma_f32_16x16x32_bf16 v[26:29], v[170:173], v[216:219], v[26:29]
	v_mfma_f32_16x16x32_bf16 v[14:17], v[152:155], v[224:227], v[14:17]
	v_mfma_f32_16x16x32_bf16 v[10:13], v[170:173], v[224:227], v[10:13]
	v_mfma_f32_16x16x32_bf16 v[62:65], v[166:169], v[204:207], v[62:65]
	v_mfma_f32_16x16x32_bf16 v[58:61], v[174:177], v[204:207], v[58:61]
	v_mfma_f32_16x16x32_bf16 v[46:49], v[166:169], v[212:215], v[46:49]
	v_mfma_f32_16x16x32_bf16 v[42:45], v[174:177], v[212:215], v[42:45]
	v_mfma_f32_16x16x32_bf16 v[30:33], v[166:169], v[220:223], v[30:33]
	v_mfma_f32_16x16x32_bf16 v[26:29], v[174:177], v[220:223], v[26:29]
	v_mfma_f32_16x16x32_bf16 v[14:17], v[166:169], v[228:231], v[14:17]
	v_mfma_f32_16x16x32_bf16 v[10:13], v[174:177], v[228:231], v[10:13]
	v_mfma_f32_16x16x32_bf16 v[54:57], v[178:181], v[200:203], v[54:57]
	v_mfma_f32_16x16x32_bf16 v[50:53], v[186:189], v[200:203], v[50:53]
	v_mfma_f32_16x16x32_bf16 v[38:41], v[178:181], v[208:211], v[38:41]
	v_mfma_f32_16x16x32_bf16 v[34:37], v[186:189], v[208:211], v[34:37]
	v_mfma_f32_16x16x32_bf16 v[22:25], v[178:181], v[216:219], v[22:25]
	v_mfma_f32_16x16x32_bf16 v[18:21], v[186:189], v[216:219], v[18:21]
	v_mfma_f32_16x16x32_bf16 v[6:9], v[178:181], v[224:227], v[6:9]
	v_mfma_f32_16x16x32_bf16 v[2:5], v[186:189], v[224:227], v[2:5]
	v_mfma_f32_16x16x32_bf16 v[54:57], v[182:185], v[204:207], v[54:57]
	v_mfma_f32_16x16x32_bf16 v[50:53], v[190:193], v[204:207], v[50:53]
	v_mfma_f32_16x16x32_bf16 v[38:41], v[182:185], v[212:215], v[38:41]
	v_mfma_f32_16x16x32_bf16 v[34:37], v[190:193], v[212:215], v[34:37]
	v_mfma_f32_16x16x32_bf16 v[22:25], v[182:185], v[220:223], v[22:25]
	v_mfma_f32_16x16x32_bf16 v[18:21], v[190:193], v[220:223], v[18:21]
	v_mfma_f32_16x16x32_bf16 v[6:9], v[182:185], v[228:231], v[6:9]
	v_mfma_f32_16x16x32_bf16 v[2:5], v[190:193], v[228:231], v[2:5]
	s_barrier
	s_add_i32 s69, s69, 2
	s_add_u32 s30, s30, 0x100
	s_addc_u32 s31, s31, 0
	s_add_u32 s67, s67, 0x100
	s_addc_u32 s68, s68, 0
	s_cmp_gt_u32 s69, 29
	s_cbranch_scc0 .LBB0_139
	s_and_b64 vcc, exec, s[16:17]
	s_cbranch_vccz .LBB0_142
	s_barrier

; __device__ __forceinline__ unsigned xb_ld(unsigned* p)              { return __hip_atomic_load(p, __ATOMIC_RELAXED, __HIP_MEMORY_SCOPE_AGENT); }
; __device__ __forceinline__ void xcd_barrier_complete(unsigned* bar, unsigned x, unsigned& nloc, unsigned& nx) {
;     const unsigned G = gridDim.x * gridDim.y * gridDim.z;
;     unsigned sum, cnt, mine, sp = 0u;
;     for (;;) {
;         sum = 0u; cnt = 0u; mine = 0u;
; #pragma unroll
;         for (unsigned j = 0; j < 16; ++j) { const unsigned c = xb_ld(&bar[XB_XCNT(j)]); sum += c; cnt += (c > 0u) ? 1u : 0u; mine = (j == x) ? c : mine; }
; __device__ __forceinline__ void xcd_barrier(const XcdBarrier& b) {
;     asm volatile("s_waitcnt vmcnt(0)" ::: "memory");
;     __syncthreads();
;     if (threadIdx.x == 0) {
;         unsigned* bar = b.bar;
;         __builtin_amdgcn_s_waitcnt(0);
;         unsigned nloc = b.st[0], nx = b.st[1];
;         if (nloc == 0u) { xcd_barrier_complete(bar, b.x, nloc, nx); b.st[0] = nloc; b.st[1] = nx; }
.LBB0_192:
	v_readlane_b32 s0, v252, 30
	v_readlane_b32 s12, v253, 2
	s_add_i32 s21, s0, 2
	v_readlane_b32 s15, v253, 5
	s_cmp_ge_i32 s21, s15
	v_readlane_b32 s13, v253, 3
	v_readlane_b32 s14, v253, 4
	s_cbranch_scc1 .LBB0_246
	s_waitcnt vmcnt(0)
	s_waitcnt vmcnt(0) lgkmcnt(0)
	s_barrier
	s_setprio 0
	s_and_saveexec_b64 s[0:1], s[80:81]
	s_cbranch_execz .LBB0_245
	v_readlane_b32 s4, v254, 61
	s_waitcnt vmcnt(0) expcnt(0) lgkmcnt(0)
	s_nop 0
	v_mov_b32_e32 v2, s4
	ds_read_b32 v4, v2
	v_readlane_b32 s4, v254, 62
	s_waitcnt lgkmcnt(0)
	v_cmp_ne_u32_e32 vcc, 0, v4
	v_mov_b32_e32 v2, s4
	ds_read_b32 v2, v2
	s_cbranch_vccnz .LBB0_209
	v_readlane_b32 s12, v253, 6
	v_readlane_b32 s13, v253, 7
	s_load_dwordx2 s[4:5], s[12:13], 0x0
	s_nop 0
	s_load_dword s12, s[12:13], 0x8
	s_mov_b32 s17, 1
	s_waitcnt lgkmcnt(0)
	s_mul_i32 s16, s5, s4
	s_mul_i32 s16, s16, s12
	s_branch .LBB0_197

; __device__ __forceinline__ unsigned xb_ld(unsigned* p)              { return __hip_atomic_load(p, __ATOMIC_RELAXED, __HIP_MEMORY_SCOPE_AGENT); }
; __device__ __forceinline__ void xcd_barrier_complete(unsigned* bar, unsigned x, unsigned& nloc, unsigned& nx) {
;     const unsigned G = gridDim.x * gridDim.y * gridDim.z;
;     unsigned sum, cnt, mine, sp = 0u;
;     for (;;) {
;         sum = 0u; cnt = 0u; mine = 0u;
; #pragma unroll
;         for (unsigned j = 0; j < 16; ++j) { const unsigned c = xb_ld(&bar[XB_XCNT(j)]); sum += c; cnt += (c > 0u) ? 1u : 0u; mine = (j == x) ? c : mine; }
; __device__ __forceinline__ void xcd_barrier(const XcdBarrier& b) {
;     asm volatile("s_waitcnt vmcnt(0)" ::: "memory");
;     __syncthreads();
;     if (threadIdx.x == 0) {
;         unsigned* bar = b.bar;
;         __builtin_amdgcn_s_waitcnt(0);
;         unsigned nloc = b.st[0], nx = b.st[1];
;         if (nloc == 0u) { xcd_barrier_complete(bar, b.x, nloc, nx); b.st[0] = nloc; b.st[1] = nx; }
.LBB0_323:
	v_readlane_b32 s0, v252, 30
	v_readlane_b32 s12, v253, 2
	s_add_i32 s21, s0, 3
	v_readlane_b32 s15, v253, 5
	s_cmp_ge_i32 s21, s15
	v_readlane_b32 s13, v253, 3
	v_readlane_b32 s14, v253, 4
	s_cbranch_scc1 .LBB0_335
	s_waitcnt vmcnt(0)
	s_waitcnt lgkmcnt(0)
	s_barrier
	s_setprio 0
	s_and_saveexec_b64 s[0:1], s[80:81]
	s_mov_b64 s[62:63], s[88:89]
	s_cbranch_execz .LBB0_377
	v_readlane_b32 s4, v254, 61
	s_waitcnt vmcnt(0) expcnt(0) lgkmcnt(0)
	s_nop 0
	v_mov_b32_e32 v2, s4
	ds_read_b32 v4, v2
	v_readlane_b32 s4, v254, 62
	s_waitcnt lgkmcnt(0)
	v_cmp_ne_u32_e32 vcc, 0, v4
	v_mov_b32_e32 v2, s4
	ds_read_b32 v2, v2
	s_cbranch_vccnz .LBB0_341
	v_readlane_b32 s12, v253, 6
	v_readlane_b32 s13, v253, 7
	s_load_dwordx2 s[4:5], s[12:13], 0x0
	s_nop 0
	s_load_dword s12, s[12:13], 0x8
	s_mov_b32 s17, 1
	s_waitcnt lgkmcnt(0)
	s_mul_i32 s16, s5, s4
	s_mul_i32 s16, s16, s12
	s_branch .LBB0_328

; __device__ __forceinline__ unsigned xb_ld(unsigned* p)              { return __hip_atomic_load(p, __ATOMIC_RELAXED, __HIP_MEMORY_SCOPE_AGENT); }
; __device__ __forceinline__ void xcd_barrier_complete(unsigned* bar, unsigned x, unsigned& nloc, unsigned& nx) {
;     const unsigned G = gridDim.x * gridDim.y * gridDim.z;
;     unsigned sum, cnt, mine, sp = 0u;
;     for (;;) {
;         sum = 0u; cnt = 0u; mine = 0u;
; #pragma unroll
;         for (unsigned j = 0; j < 16; ++j) { const unsigned c = xb_ld(&bar[XB_XCNT(j)]); sum += c; cnt += (c > 0u) ? 1u : 0u; mine = (j == x) ? c : mine; }
; __device__ __forceinline__ void xcd_barrier(const XcdBarrier& b) {
;     asm volatile("s_waitcnt vmcnt(0)" ::: "memory");
;     __syncthreads();
;     if (threadIdx.x == 0) {
;         unsigned* bar = b.bar;
;         __builtin_amdgcn_s_waitcnt(0);
;         unsigned nloc = b.st[0], nx = b.st[1];
;         if (nloc == 0u) { xcd_barrier_complete(bar, b.x, nloc, nx); b.st[0] = nloc; b.st[1] = nx; }
.LBB0_414:
	v_readlane_b32 s0, v252, 30
	v_readlane_b32 s12, v253, 2
	s_add_i32 s21, s0, 4
	v_readlane_b32 s15, v253, 5
	s_cmp_ge_i32 s21, s15
	v_readlane_b32 s13, v253, 3
	v_readlane_b32 s14, v253, 4
	s_cbranch_scc1 .LBB0_472
	s_waitcnt vmcnt(0)
	s_barrier
	s_setprio 0
	s_and_saveexec_b64 s[0:1], s[80:81]
	s_cbranch_execz .LBB0_471
	v_readlane_b32 s4, v254, 61
	s_waitcnt vmcnt(0) expcnt(0) lgkmcnt(0)
	s_nop 0
	v_mov_b32_e32 v2, s4
	ds_read_b32 v4, v2
	v_readlane_b32 s4, v254, 62
	s_waitcnt lgkmcnt(0)
	v_cmp_ne_u32_e32 vcc, 0, v4
	v_mov_b32_e32 v2, s4
	ds_read_b32 v2, v2
	s_cbranch_vccnz .LBB0_435
	v_readlane_b32 s12, v253, 6
	v_readlane_b32 s13, v253, 7
	s_load_dwordx2 s[4:5], s[12:13], 0x0
	s_nop 0
	s_load_dword s12, s[12:13], 0x8
	s_mov_b32 s17, 1
	s_waitcnt lgkmcnt(0)
	s_mul_i32 s16, s5, s4
	s_mul_i32 s16, s16, s12
	s_branch .LBB0_419

; __device__ __forceinline__ unsigned xb_ld(unsigned* p)              { return __hip_atomic_load(p, __ATOMIC_RELAXED, __HIP_MEMORY_SCOPE_AGENT); }
; __device__ __forceinline__ void xcd_barrier_complete(unsigned* bar, unsigned x, unsigned& nloc, unsigned& nx) {
;     const unsigned G = gridDim.x * gridDim.y * gridDim.z;
;     unsigned sum, cnt, mine, sp = 0u;
;     for (;;) {
;         sum = 0u; cnt = 0u; mine = 0u;
; #pragma unroll
;         for (unsigned j = 0; j < 16; ++j) { const unsigned c = xb_ld(&bar[XB_XCNT(j)]); sum += c; cnt += (c > 0u) ? 1u : 0u; mine = (j == x) ? c : mine; }
; __device__ __forceinline__ void xcd_barrier(const XcdBarrier& b) {
;     asm volatile("s_waitcnt vmcnt(0)" ::: "memory");
;     __syncthreads();
;     if (threadIdx.x == 0) {
;         unsigned* bar = b.bar;
;         __builtin_amdgcn_s_waitcnt(0);
;         unsigned nloc = b.st[0], nx = b.st[1];
;         if (nloc == 0u) { xcd_barrier_complete(bar, b.x, nloc, nx); b.st[0] = nloc; b.st[1] = nx; }
.LBB0_597:
	v_readlane_b32 s0, v252, 30
	v_readlane_b32 s12, v253, 2
	s_add_i32 s21, s0, 5
	v_readlane_b32 s15, v253, 5
	s_cmp_ge_i32 s21, s15
	v_readlane_b32 s13, v253, 3
	v_readlane_b32 s14, v253, 4
	s_cbranch_scc1 .LBB0_651
	s_waitcnt vmcnt(0)
	s_waitcnt vmcnt(0) lgkmcnt(0)
	s_barrier
	s_setprio 0
	s_and_saveexec_b64 s[0:1], s[80:81]
	s_cbranch_execz .LBB0_650
	v_readlane_b32 s4, v254, 61
	s_waitcnt vmcnt(0) expcnt(0) lgkmcnt(0)
	s_nop 0
	v_mov_b32_e32 v2, s4
	ds_read_b32 v4, v2
	v_readlane_b32 s4, v254, 62
	s_waitcnt lgkmcnt(0)
	v_cmp_ne_u32_e32 vcc, 0, v4
	v_mov_b32_e32 v2, s4
	ds_read_b32 v2, v2
	s_cbranch_vccnz .LBB0_614
	v_readlane_b32 s12, v253, 6
	v_readlane_b32 s13, v253, 7
	s_load_dwordx2 s[4:5], s[12:13], 0x0
	s_nop 0
	s_load_dword s12, s[12:13], 0x8
	s_mov_b32 s17, 1
	s_waitcnt lgkmcnt(0)
	s_mul_i32 s16, s5, s4
	s_mul_i32 s16, s16, s12
	s_branch .LBB0_602

; #define PG8_STAGE(bufoff, gbase, voff) do { _Pragma("unroll") for (int _i = 0; _i < 2; ++_i) \
;         __builtin_amdgcn_global_load_lds((const unsigned*)((const char*)(gbase) + (voff)[_i]), (PG8_LAS unsigned*)(lds + (bufoff) + ldsw + _i * 8192), 16, 0, 0); } while (0)
; #define PG8_WAIT_V(n) asm volatile("s_waitcnt vmcnt(" #n ")" ::: "memory")
; #define PG8_BAR __builtin_amdgcn_s_barrier()
; template <class Epi, class Sched, bool ALIGN_EPI = false, bool SP2 = false>
; __device__ __forceinline__ void gemm_phase(PG8_LAS unsigned char* lds, const Gemm g, const Sched& S, const Epi& E) {
;     ...
;     for (int i = 0; i < 2; ++i) { int R, C; stage_rc(tid * 16 + i * 8192, R, C); const int Rb = Epi::PERM ? ((R & ~31) + perm32(R & 31)) : R;
;         voffA[i] = (unsigned)(R * K + C) * 2u; voffB[i] = (unsigned)(Rb * K + C) * 2u; }
;     const size_t kstep = (size_t)(BK * 2);
;     const size_t hstep = (size_t)HALF * K * 2;
;     const size_t tstep = 2 * hstep;
;     const unsigned ldsw = (unsigned)wid * 1024u;
;     const int aoff = lds_byte(wr * 64 + fr, fq * 8), boff = lds_byte(wc * 32 + fr, fq * 8);
;     ...
;         PG8_WAIT_V(2); PG8_BAR;
;         PG8_STAGE(PG8_SB(1, 0), cB + kstep, voffB); PG8_STAGE(PG8_SA(1, 0), cA + kstep, voffA); PG8_STAGE(PG8_SB(1, 1), cB + hstep + kstep, voffB);
;         PG8_WAIT_V(6); PG8_BAR;
.LBB0_657:
	s_add_u32 s12, s14, 0x1d800000
	s_addc_u32 s13, s15, 0
	v_bfe_u32 v17, v16, 4, 2
	s_add_u32 s14, s14, 0xc00000
	v_and_b32_e32 v18, 15, v16
	v_lshlrev_b32_e32 v20, 4, v17
	v_lshlrev_b32_e32 v16, 2, v16
	s_addc_u32 s15, s15, 0
	s_and_b32 s53, s18, 3
	v_lshl_or_b32 v161, s17, 6, v18
	v_lshl_or_b32 v18, v18, 6, v20
	s_lshl_b32 s17, s17, 13
	v_and_b32_e32 v16, 32, v16
	s_add_i32 m0, s48, 0x18000
	v_lshl_add_u64 v[8:9], v[8:9], 0, s[10:11]
	v_bitop3_b32 v20, v18, s17, v16 bitop3:0xde
	s_lshl_b32 s17, s53, 12
	s_waitcnt vmcnt(2)
	s_barrier
	global_load_lds_dwordx4 v[8:9], off
	v_lshl_add_u64 v[6:7], v[6:7], 0, s[10:11]
	s_add_i32 m0, s48, 0x1a000
	s_add_i32 s54, s48, 0x8000
	s_add_i32 s55, s48, 0xa000
	global_load_lds_dwordx4 v[6:7], off
	v_lshl_add_u64 v[2:3], v[2:3], 0, s[10:11]
	s_mov_b32 m0, s54
	s_add_u32 s18, s30, 0x80080
	global_load_lds_dwordx4 v[2:3], off
	v_lshl_add_u64 v[2:3], v[4:5], 0, s[10:11]
	s_mov_b32 m0, s55
	s_addc_u32 s19, s31, 0
	global_load_lds_dwordx4 v[2:3], off
	s_add_i32 m0, s48, 0x1c000
	v_lshl_add_u64 v[2:3], s[18:19], 0, v[158:159]
	global_load_lds_dwordx4 v[2:3], off
	v_lshl_add_u64 v[2:3], s[18:19], 0, v[166:167]
	s_add_i32 m0, s48, 0x1e000
	v_lshlrev_b32_e32 v19, 3, v17
	global_load_lds_dwordx4 v[2:3], off
	v_lshlrev_b32_e32 v2, 15, v14
	v_and_b32_e32 v2, 0xffff0000, v2
	v_lshl_add_u32 v2, v13, 12, v2
	v_and_b32_e32 v3, 1, v14
	v_lshl_or_b32 v2, v3, 6, v2
	v_lshl_add_u32 v172, v15, 1, v2
	v_lshlrev_b32_e32 v2, 15, v10
	v_and_b32_e32 v2, 0xffff0000, v2
	s_waitcnt vmcnt(6)
	v_lshl_add_u32 v2, v11, 12, v2
	v_and_b32_e32 v3, 1, v10
	s_cmpk_lt_u32 s16, 0x100
	v_lshl_or_b32 v2, v3, 6, v2
	v_readlane_b32 s18, v252, 22
	v_bitop3_b32 v199, v18, s17, v16 bitop3:0xde
	v_lshl_or_b32 v200, s53, 5, v19
	s_cselect_b64 s[16:17], -1, 0
	s_cbranch_scc1 .Lsp_2
	s_setprio 1
.Lsp_2:
	s_mov_b32 s56, 0
	v_cmp_eq_u32_e64 s[42:43], 0, v17
	s_waitcnt lgkmcnt(0)
	s_ashr_i32 s57, s52, 31
	v_mov_b32_e32 v173, v159
	v_lshl_add_u32 v174, v12, 1, v2
	v_mov_b32_e32 v175, v159
	v_add_u32_e32 v201, 0, v20
	v_readlane_b32 s34, v254, 48
	s_mov_b32 s58, s18
	s_barrier
	v_readlane_b32 s19, v252, 23
	s_branch .LBB0_660

; #define PG8_STAGE(bufoff, gbase, voff) do { _Pragma("unroll") for (int _i = 0; _i < 2; ++_i) \
;         __builtin_amdgcn_global_load_lds((const unsigned*)((const char*)(gbase) + (voff)[_i]), (PG8_LAS unsigned*)(lds + (bufoff) + ldsw + _i * 8192), 16, 0, 0); } while (0)
; #define PG8_LDA(dst, b, h) do { _Pragma("unroll") for (int m = 0; m < 4; ++m) _Pragma("unroll") for (int k = 0; k < 2; ++k) dst[m][k] = *(const PG8_LAS bf16x8*)(lds + PG8_SA(b, h) + aoff + m * 2048 + k * 1024); } while (0)
; #define PG8_LDB(dst, b, h) do { _Pragma("unroll") for (int n = 0; n < 2; ++n) _Pragma("unroll") for (int k = 0; k < 2; ++k) dst[n][k] = *(const PG8_LAS bf16x8*)(lds + PG8_SB(b, h) + boff + n * 2048 + k * 1024); } while (0)
; #define PG8_MMA(ai, bj, At, Bt) do { __builtin_amdgcn_s_setprio(1); _Pragma("unroll") for (int m = 0; m < 4; ++m) _Pragma("unroll") for (int n = 0; n < 2; ++n) _Pragma("unroll") for (int k = 0; k < 2; ++k) \
;         acc[ai][bj][m][n] = __builtin_amdgcn_mfma_f32_16x16x32_bf16(Bt[n][k], At[m][k], acc[ai][bj][m][n], 0, 0, 0); __builtin_amdgcn_s_setprio(0); } while (0)
; #define PG8_WAIT_V(n) asm volatile("s_waitcnt vmcnt(" #n ")" ::: "memory")
; #define PG8_BAR __builtin_amdgcn_s_barrier()
; template <class Epi, class Sched, bool ALIGN_EPI = false, bool SP2 = false>
; __device__ __forceinline__ void gemm_phase(PG8_LAS unsigned char* lds, const Gemm g, const Sched& S, const Epi& E) {
;     ...
;         for (int t = 0; t < nt; t += 2) {
;             const bool last = (t == nt - 2);
;             const char* a1 = cA + (size_t)(t + 1) * kstep;
;             const char* a2 = last ? nA : cA + (size_t)(t + 2) * kstep; const char* b2 = last ? nB : cB + (size_t)(t + 2) * kstep;
;             const char* a3 = a2 + kstep; const char* b3 = b2 + kstep;
;             if (last && has_next) S.a_ready(nxt);
;             if constexpr (SP2) {
;             PG8_LDB(B0, 0, 0); PG8_LDB(B1, 0, 1); PG8_SCHED; PG8_LDA(At, 0, 0); PG8_STAGE(PG8_SA(1, 1), a1 + hstep, voffA);
;             PG8_WAIT_V(8); PG8_WAIT_L(0); PG8_BAR; PG8_MMA(0, 0, At, B0); PG8_MMA(0, 1, At, B1); PG8_BAR; PG8_SCHED;
;             PG8_LDA(At, 0, 1); PG8_STAGE(PG8_SB(0, 0), b2, voffB); PG8_STAGE(PG8_SB(0, 1), b2 + hstep, voffB); PG8_STAGE(PG8_SA(0, 0), a2, voffA);
;             PG8_WAIT_V(8); PG8_WAIT_L(0); PG8_BAR; PG8_MMA(1, 0, At, B0); PG8_MMA(1, 1, At, B1); PG8_BAR; PG8_SCHED;
.LBB0_667:
	s_add_u32 s30, s0, 0xfff80080
	s_addc_u32 s31, s1, -1
	s_add_i32 s66, 0, 0x10000
	s_cmp_eq_u32 s63, 28
	s_cselect_b32 s37, s23, s31
	s_cselect_b32 s36, s59, s30
	s_cselect_b32 s31, s19, s62
	s_cselect_b32 s30, s60, s61
	s_add_i32 s68, 0, 0x14000
	v_add_u32_e32 v142, s66, v199
	v_add_u32_e32 v162, s68, v199
	ds_read_b128 v[130:133], v142
	ds_read_b128 v[134:137], v142 offset:1024
	ds_read_b128 v[138:141], v142 offset:2048
	ds_read_b128 v[142:145], v142 offset:3072
	ds_read_b128 v[146:149], v162
	ds_read_b128 v[150:153], v162 offset:1024
	ds_read_b128 v[154:157], v162 offset:2048
	ds_read_b128 v[162:165], v162 offset:3072
	s_add_u32 s98, s0, 0xfff80000
	s_addc_u32 s99, s1, -1
	s_mov_b32 m0, s54
	s_nop 0
	global_load_lds_dwordx4 v172, s[98:99]
	s_mov_b32 m0, s55
	s_nop 0
	global_load_lds_dwordx4 v174, s[98:99]
	s_add_i32 m0, s48, 0xc000
	ds_read_b128 v[176:179], v201
	ds_read_b128 v[180:183], v201 offset:1024
	ds_read_b128 v[184:187], v201 offset:2048
	ds_read_b128 v[188:191], v201 offset:3072
	ds_read_b128 v[202:205], v201 offset:4096
	ds_read_b128 v[206:209], v201 offset:5120
	ds_read_b128 v[210:213], v201 offset:6144
	ds_read_b128 v[214:217], v201 offset:7168
	global_load_lds_dwordx4 v172, s[0:1]
	s_add_i32 m0, s48, 0xe000
	s_nop 0
	global_load_lds_dwordx4 v174, s[0:1]
	s_waitcnt vmcnt(8)
	s_waitcnt lgkmcnt(0)
	s_barrier
	s_waitcnt lgkmcnt(0)
	v_mfma_f32_16x16x32_bf16 v[126:129], v[130:133], v[176:179], v[126:129]
	v_mfma_f32_16x16x32_bf16 v[122:125], v[138:141], v[176:179], v[122:125]
	v_mfma_f32_16x16x32_bf16 v[110:113], v[130:133], v[184:187], v[110:113]
	v_mfma_f32_16x16x32_bf16 v[106:109], v[138:141], v[184:187], v[106:109]
	v_mfma_f32_16x16x32_bf16 v[94:97], v[130:133], v[202:205], v[94:97]
	v_mfma_f32_16x16x32_bf16 v[90:93], v[138:141], v[202:205], v[90:93]
	v_mfma_f32_16x16x32_bf16 v[78:81], v[130:133], v[210:213], v[78:81]
	v_mfma_f32_16x16x32_bf16 v[74:77], v[138:141], v[210:213], v[74:77]
	v_mfma_f32_16x16x32_bf16 v[126:129], v[134:137], v[180:183], v[126:129]
	v_mfma_f32_16x16x32_bf16 v[122:125], v[142:145], v[180:183], v[122:125]
	v_mfma_f32_16x16x32_bf16 v[110:113], v[134:137], v[188:191], v[110:113]
	v_mfma_f32_16x16x32_bf16 v[106:109], v[142:145], v[188:191], v[106:109]
	v_mfma_f32_16x16x32_bf16 v[94:97], v[134:137], v[206:209], v[94:97]
	v_mfma_f32_16x16x32_bf16 v[90:93], v[142:145], v[206:209], v[90:93]
	v_mfma_f32_16x16x32_bf16 v[78:81], v[134:137], v[214:217], v[78:81]
	v_mfma_f32_16x16x32_bf16 v[74:77], v[142:145], v[214:217], v[74:77]
	v_mfma_f32_16x16x32_bf16 v[118:121], v[146:149], v[176:179], v[118:121]
	v_mfma_f32_16x16x32_bf16 v[114:117], v[154:157], v[176:179], v[114:117]
	v_mfma_f32_16x16x32_bf16 v[102:105], v[146:149], v[184:187], v[102:105]
	v_mfma_f32_16x16x32_bf16 v[98:101], v[154:157], v[184:187], v[98:101]
	v_mfma_f32_16x16x32_bf16 v[86:89], v[146:149], v[202:205], v[86:89]
	v_mfma_f32_16x16x32_bf16 v[82:85], v[154:157], v[202:205], v[82:85]
	v_mfma_f32_16x16x32_bf16 v[70:73], v[146:149], v[210:213], v[70:73]
	v_mfma_f32_16x16x32_bf16 v[66:69], v[154:157], v[210:213], v[66:69]
	v_mfma_f32_16x16x32_bf16 v[118:121], v[150:153], v[180:183], v[118:121]
	v_mfma_f32_16x16x32_bf16 v[114:117], v[162:165], v[180:183], v[114:117]
	v_mfma_f32_16x16x32_bf16 v[102:105], v[150:153], v[188:191], v[102:105]
	v_mfma_f32_16x16x32_bf16 v[98:101], v[162:165], v[188:191], v[98:101]
	v_mfma_f32_16x16x32_bf16 v[86:89], v[150:153], v[206:209], v[86:89]
	v_mfma_f32_16x16x32_bf16 v[82:85], v[162:165], v[206:209], v[82:85]
	v_mfma_f32_16x16x32_bf16 v[70:73], v[150:153], v[214:217], v[70:73]
	v_mfma_f32_16x16x32_bf16 v[66:69], v[162:165], v[214:217], v[66:69]
	s_barrier
	s_add_i32 s66, s66, s47
	s_mov_b32 m0, s66
	ds_read_b128 v[176:179], v201 offset:16384
	ds_read_b128 v[180:183], v201 offset:17408
	ds_read_b128 v[184:187], v201 offset:18432
	ds_read_b128 v[188:191], v201 offset:19456
	ds_read_b128 v[202:205], v201 offset:20480
	ds_read_b128 v[206:209], v201 offset:21504
	ds_read_b128 v[210:213], v201 offset:22528
	ds_read_b128 v[214:217], v201 offset:23552
	global_load_lds_dwordx4 v158, s[30:31]
	s_add_i32 m0, s66, 0x2000
	s_add_u32 s66, s30, 0x80000
	s_addc_u32 s67, s31, 0
	s_add_i32 s68, s68, s47
	global_load_lds_dwordx4 v166, s[30:31]
	s_mov_b32 m0, s68
	s_nop 0
	global_load_lds_dwordx4 v158, s[66:67]
	s_add_i32 m0, s68, 0x2000
	s_nop 0
	global_load_lds_dwordx4 v166, s[66:67]
	s_waitcnt vmcnt(6)
	s_waitcnt lgkmcnt(0)
	s_barrier
	s_waitcnt lgkmcnt(0)
	v_mfma_f32_16x16x32_bf16 v[62:65], v[130:133], v[176:179], v[62:65]
	v_mfma_f32_16x16x32_bf16 v[58:61], v[138:141], v[176:179], v[58:61]
	v_mfma_f32_16x16x32_bf16 v[46:49], v[130:133], v[184:187], v[46:49]
	v_mfma_f32_16x16x32_bf16 v[42:45], v[138:141], v[184:187], v[42:45]
	v_mfma_f32_16x16x32_bf16 v[30:33], v[130:133], v[202:205], v[30:33]
	v_mfma_f32_16x16x32_bf16 v[26:29], v[138:141], v[202:205], v[26:29]
	v_mfma_f32_16x16x32_bf16 v[14:17], v[130:133], v[210:213], v[14:17]
	v_mfma_f32_16x16x32_bf16 v[10:13], v[138:141], v[210:213], v[10:13]
	v_mfma_f32_16x16x32_bf16 v[62:65], v[134:137], v[180:183], v[62:65]
	v_mfma_f32_16x16x32_bf16 v[58:61], v[142:145], v[180:183], v[58:61]
	v_mfma_f32_16x16x32_bf16 v[46:49], v[134:137], v[188:191], v[46:49]
	v_mfma_f32_16x16x32_bf16 v[42:45], v[142:145], v[188:191], v[42:45]
	v_mfma_f32_16x16x32_bf16 v[30:33], v[134:137], v[206:209], v[30:33]
	v_mfma_f32_16x16x32_bf16 v[26:29], v[142:145], v[206:209], v[26:29]
	v_mfma_f32_16x16x32_bf16 v[14:17], v[134:137], v[214:217], v[14:17]
	v_mfma_f32_16x16x32_bf16 v[10:13], v[142:145], v[214:217], v[10:13]
	v_mfma_f32_16x16x32_bf16 v[54:57], v[146:149], v[176:179], v[54:57]
	v_mfma_f32_16x16x32_bf16 v[50:53], v[154:157], v[176:179], v[50:53]
	v_mfma_f32_16x16x32_bf16 v[38:41], v[146:149], v[184:187], v[38:41]
	v_mfma_f32_16x16x32_bf16 v[34:37], v[154:157], v[184:187], v[34:37]
	v_mfma_f32_16x16x32_bf16 v[22:25], v[146:149], v[202:205], v[22:25]
	v_mfma_f32_16x16x32_bf16 v[18:21], v[154:157], v[202:205], v[18:21]
	v_mfma_f32_16x16x32_bf16 v[6:9], v[146:149], v[210:213], v[6:9]
	v_mfma_f32_16x16x32_bf16 v[2:5], v[154:157], v[210:213], v[2:5]
	v_mfma_f32_16x16x32_bf16 v[54:57], v[150:153], v[180:183], v[54:57]
	v_mfma_f32_16x16x32_bf16 v[50:53], v[162:165], v[180:183], v[50:53]
	v_mfma_f32_16x16x32_bf16 v[38:41], v[150:153], v[188:191], v[38:41]
	v_mfma_f32_16x16x32_bf16 v[34:37], v[162:165], v[188:191], v[34:37]
	v_mfma_f32_16x16x32_bf16 v[22:25], v[150:153], v[206:209], v[22:25]
	v_mfma_f32_16x16x32_bf16 v[18:21], v[162:165], v[206:209], v[18:21]
	v_mfma_f32_16x16x32_bf16 v[6:9], v[150:153], v[214:217], v[6:9]
	v_mfma_f32_16x16x32_bf16 v[2:5], v[162:165], v[214:217], v[2:5]
	s_barrier
; #define PG8_STAGE(bufoff, gbase, voff) do { _Pragma("unroll") for (int _i = 0; _i < 2; ++_i) \
;         __builtin_amdgcn_global_load_lds((const unsigned*)((const char*)(gbase) + (voff)[_i]), (PG8_LAS unsigned*)(lds + (bufoff) + ldsw + _i * 8192), 16, 0, 0); } while (0)
; #define PG8_LDA(dst, b, h) do { _Pragma("unroll") for (int m = 0; m < 4; ++m) _Pragma("unroll") for (int k = 0; k < 2; ++k) dst[m][k] = *(const PG8_LAS bf16x8*)(lds + PG8_SA(b, h) + aoff + m * 2048 + k * 1024); } while (0)
; #define PG8_LDB(dst, b, h) do { _Pragma("unroll") for (int n = 0; n < 2; ++n) _Pragma("unroll") for (int k = 0; k < 2; ++k) dst[n][k] = *(const PG8_LAS bf16x8*)(lds + PG8_SB(b, h) + boff + n * 2048 + k * 1024); } while (0)
; #define PG8_MMA(ai, bj, At, Bt) do { __builtin_amdgcn_s_setprio(1); _Pragma("unroll") for (int m = 0; m < 4; ++m) _Pragma("unroll") for (int n = 0; n < 2; ++n) _Pragma("unroll") for (int k = 0; k < 2; ++k) \
;         acc[ai][bj][m][n] = __builtin_amdgcn_mfma_f32_16x16x32_bf16(Bt[n][k], At[m][k], acc[ai][bj][m][n], 0, 0, 0); __builtin_amdgcn_s_setprio(0); } while (0)
; #define PG8_WAIT_V(n) asm volatile("s_waitcnt vmcnt(" #n ")" ::: "memory")
; #define PG8_WAIT_L(n) asm volatile("s_waitcnt lgkmcnt(" #n ")" ::: "memory")
; #define PG8_BAR __builtin_amdgcn_s_barrier()
; #define PG8_SCHED __builtin_amdgcn_sched_barrier(0)
; template <class Epi, class Sched, bool ALIGN_EPI = false, bool SP2 = false>
; __device__ __forceinline__ void gemm_phase(PG8_LAS unsigned char* lds, const Gemm g, const Sched& S, const Epi& E) {
;     ...
;             PG8_LDB(B0, 1, 0); PG8_LDB(B1, 1, 1); PG8_SCHED; PG8_LDA(At, 1, 0); PG8_STAGE(PG8_SA(0, 1), a2 + hstep, voffA);
;             PG8_WAIT_V(8); PG8_WAIT_L(0); PG8_BAR; PG8_MMA(0, 0, At, B0); PG8_MMA(0, 1, At, B1); PG8_BAR; PG8_SCHED;
;             PG8_LDA(At, 1, 1); PG8_STAGE(PG8_SB(1, 0), b3, voffB); PG8_STAGE(PG8_SB(1, 1), b3 + hstep, voffB); PG8_STAGE(PG8_SA(1, 0), a3, voffA);
;             PG8_WAIT_V(8); PG8_WAIT_L(0); PG8_BAR; PG8_MMA(1, 0, At, B0); PG8_MMA(1, 1, At, B1); PG8_BAR; PG8_SCHED;
;     ...
;         if constexpr (ALIGN_EPI) { if (wr == 0) PG8_BAR; }
	s_add_i32 s66, 0, 0x18000
	s_add_i32 s67, 0, 0x1c000
	v_add_u32_e32 v142, s66, v199
	v_add_u32_e32 v162, s67, v199
	ds_read_b128 v[130:133], v142
	ds_read_b128 v[134:137], v142 offset:1024
	ds_read_b128 v[138:141], v142 offset:2048
	ds_read_b128 v[142:145], v142 offset:3072
	ds_read_b128 v[146:149], v162
	ds_read_b128 v[150:153], v162 offset:1024
	ds_read_b128 v[154:157], v162 offset:2048
	ds_read_b128 v[162:165], v162 offset:3072
	s_mov_b32 m0, s48
	s_nop 0
	global_load_lds_dwordx4 v170, s[36:37]
	s_mov_b32 m0, s49
	s_nop 0
	global_load_lds_dwordx4 v168, s[36:37]
	s_add_u32 s36, s36, 0x80000
	s_addc_u32 s37, s37, 0
	s_mov_b32 m0, s50
	ds_read_b128 v[176:179], v201 offset:32768
	ds_read_b128 v[180:183], v201 offset:33792
	ds_read_b128 v[184:187], v201 offset:34816
	ds_read_b128 v[188:191], v201 offset:35840
	ds_read_b128 v[202:205], v201 offset:36864
	ds_read_b128 v[206:209], v201 offset:37888
	ds_read_b128 v[210:213], v201 offset:38912
	ds_read_b128 v[214:217], v201 offset:39936
	global_load_lds_dwordx4 v170, s[36:37]
	s_mov_b32 m0, s51
	s_nop 0
	global_load_lds_dwordx4 v168, s[36:37]
	s_waitcnt vmcnt(8)
	s_waitcnt lgkmcnt(0)
	s_barrier
	s_waitcnt lgkmcnt(0)
	v_mfma_f32_16x16x32_bf16 v[126:129], v[130:133], v[176:179], v[126:129]
	v_mfma_f32_16x16x32_bf16 v[122:125], v[138:141], v[176:179], v[122:125]
	v_mfma_f32_16x16x32_bf16 v[110:113], v[130:133], v[184:187], v[110:113]
	v_mfma_f32_16x16x32_bf16 v[106:109], v[138:141], v[184:187], v[106:109]
	v_mfma_f32_16x16x32_bf16 v[94:97], v[130:133], v[202:205], v[94:97]
	v_mfma_f32_16x16x32_bf16 v[90:93], v[138:141], v[202:205], v[90:93]
	v_mfma_f32_16x16x32_bf16 v[78:81], v[130:133], v[210:213], v[78:81]
	v_mfma_f32_16x16x32_bf16 v[74:77], v[138:141], v[210:213], v[74:77]
	v_mfma_f32_16x16x32_bf16 v[126:129], v[134:137], v[180:183], v[126:129]
	v_mfma_f32_16x16x32_bf16 v[122:125], v[142:145], v[180:183], v[122:125]
	v_mfma_f32_16x16x32_bf16 v[110:113], v[134:137], v[188:191], v[110:113]
	v_mfma_f32_16x16x32_bf16 v[106:109], v[142:145], v[188:191], v[106:109]
	v_mfma_f32_16x16x32_bf16 v[94:97], v[134:137], v[206:209], v[94:97]
	v_mfma_f32_16x16x32_bf16 v[90:93], v[142:145], v[206:209], v[90:93]
	v_mfma_f32_16x16x32_bf16 v[78:81], v[134:137], v[214:217], v[78:81]
	v_mfma_f32_16x16x32_bf16 v[74:77], v[142:145], v[214:217], v[74:77]
	v_mfma_f32_16x16x32_bf16 v[118:121], v[146:149], v[176:179], v[118:121]
	v_mfma_f32_16x16x32_bf16 v[114:117], v[154:157], v[176:179], v[114:117]
	v_mfma_f32_16x16x32_bf16 v[102:105], v[146:149], v[184:187], v[102:105]
	v_mfma_f32_16x16x32_bf16 v[98:101], v[154:157], v[184:187], v[98:101]
	v_mfma_f32_16x16x32_bf16 v[86:89], v[146:149], v[202:205], v[86:89]
	v_mfma_f32_16x16x32_bf16 v[82:85], v[154:157], v[202:205], v[82:85]
	v_mfma_f32_16x16x32_bf16 v[70:73], v[146:149], v[210:213], v[70:73]
	v_mfma_f32_16x16x32_bf16 v[66:69], v[154:157], v[210:213], v[66:69]
	v_mfma_f32_16x16x32_bf16 v[118:121], v[150:153], v[180:183], v[118:121]
	v_mfma_f32_16x16x32_bf16 v[114:117], v[162:165], v[180:183], v[114:117]
	v_mfma_f32_16x16x32_bf16 v[102:105], v[150:153], v[188:191], v[102:105]
	v_mfma_f32_16x16x32_bf16 v[98:101], v[162:165], v[188:191], v[98:101]
	v_mfma_f32_16x16x32_bf16 v[86:89], v[150:153], v[206:209], v[86:89]
	v_mfma_f32_16x16x32_bf16 v[82:85], v[162:165], v[206:209], v[82:85]
	v_mfma_f32_16x16x32_bf16 v[70:73], v[150:153], v[214:217], v[70:73]
	v_mfma_f32_16x16x32_bf16 v[66:69], v[162:165], v[214:217], v[66:69]
	s_barrier
	s_add_i32 s36, s66, s47
	s_add_i32 m0, s36, 0xffffff80
	ds_read_b128 v[176:179], v201 offset:49152
	ds_read_b128 v[180:183], v201 offset:50176
	ds_read_b128 v[184:187], v201 offset:51200
	ds_read_b128 v[188:191], v201 offset:52224
	ds_read_b128 v[202:205], v201 offset:53248
	ds_read_b128 v[206:209], v201 offset:54272
	ds_read_b128 v[210:213], v201 offset:55296
	ds_read_b128 v[214:217], v201 offset:56320
	global_load_lds_dwordx4 v158, s[30:31] offset:128
	s_add_i32 m0, s36, 0x1f80
	s_add_i32 s36, s67, s47
	global_load_lds_dwordx4 v166, s[30:31] offset:128
	s_add_u32 s30, s30, 0x80080
	s_addc_u32 s31, s31, 0
	s_mov_b32 m0, s36
	s_nop 0
	global_load_lds_dwordx4 v158, s[30:31]
	s_add_i32 m0, s36, 0x2000
	s_nop 0
	global_load_lds_dwordx4 v166, s[30:31]
	s_waitcnt vmcnt(6)
	s_waitcnt lgkmcnt(0)
	s_barrier
	s_waitcnt lgkmcnt(0)
	v_mfma_f32_16x16x32_bf16 v[62:65], v[130:133], v[176:179], v[62:65]
	v_mfma_f32_16x16x32_bf16 v[58:61], v[138:141], v[176:179], v[58:61]
	v_mfma_f32_16x16x32_bf16 v[46:49], v[130:133], v[184:187], v[46:49]
	v_mfma_f32_16x16x32_bf16 v[42:45], v[138:141], v[184:187], v[42:45]
	v_mfma_f32_16x16x32_bf16 v[30:33], v[130:133], v[202:205], v[30:33]
	v_mfma_f32_16x16x32_bf16 v[26:29], v[138:141], v[202:205], v[26:29]
	v_mfma_f32_16x16x32_bf16 v[14:17], v[130:133], v[210:213], v[14:17]
	v_mfma_f32_16x16x32_bf16 v[10:13], v[138:141], v[210:213], v[10:13]
	v_mfma_f32_16x16x32_bf16 v[62:65], v[134:137], v[180:183], v[62:65]
	v_mfma_f32_16x16x32_bf16 v[58:61], v[142:145], v[180:183], v[58:61]
	v_mfma_f32_16x16x32_bf16 v[46:49], v[134:137], v[188:191], v[46:49]
	v_mfma_f32_16x16x32_bf16 v[42:45], v[142:145], v[188:191], v[42:45]
	v_mfma_f32_16x16x32_bf16 v[30:33], v[134:137], v[206:209], v[30:33]
	v_mfma_f32_16x16x32_bf16 v[26:29], v[142:145], v[206:209], v[26:29]
	v_mfma_f32_16x16x32_bf16 v[14:17], v[134:137], v[214:217], v[14:17]
	v_mfma_f32_16x16x32_bf16 v[10:13], v[142:145], v[214:217], v[10:13]
	v_mfma_f32_16x16x32_bf16 v[54:57], v[146:149], v[176:179], v[54:57]
	v_mfma_f32_16x16x32_bf16 v[50:53], v[154:157], v[176:179], v[50:53]
	v_mfma_f32_16x16x32_bf16 v[38:41], v[146:149], v[184:187], v[38:41]
	v_mfma_f32_16x16x32_bf16 v[34:37], v[154:157], v[184:187], v[34:37]
	v_mfma_f32_16x16x32_bf16 v[22:25], v[146:149], v[202:205], v[22:25]
	v_mfma_f32_16x16x32_bf16 v[18:21], v[154:157], v[202:205], v[18:21]
	v_mfma_f32_16x16x32_bf16 v[6:9], v[146:149], v[210:213], v[6:9]
	v_mfma_f32_16x16x32_bf16 v[2:5], v[154:157], v[210:213], v[2:5]
	v_mfma_f32_16x16x32_bf16 v[54:57], v[150:153], v[180:183], v[54:57]
	v_mfma_f32_16x16x32_bf16 v[50:53], v[162:165], v[180:183], v[50:53]
	v_mfma_f32_16x16x32_bf16 v[38:41], v[150:153], v[188:191], v[38:41]
	v_mfma_f32_16x16x32_bf16 v[34:37], v[162:165], v[188:191], v[34:37]
	v_mfma_f32_16x16x32_bf16 v[22:25], v[150:153], v[206:209], v[22:25]
	v_mfma_f32_16x16x32_bf16 v[18:21], v[162:165], v[206:209], v[18:21]
	v_mfma_f32_16x16x32_bf16 v[6:9], v[150:153], v[214:217], v[6:9]
	v_mfma_f32_16x16x32_bf16 v[2:5], v[162:165], v[214:217], v[2:5]
	s_barrier
	s_add_i32 s63, s63, 2
	s_add_u32 s0, s0, 0x100
	s_addc_u32 s1, s1, 0
	s_add_u32 s61, s61, 0x100
	s_addc_u32 s62, s62, 0
	s_cmp_gt_u32 s63, 29
	s_cbranch_scc0 .LBB0_667
	s_and_b64 vcc, exec, s[16:17]
	s_cbranch_vccz .LBB0_670
	s_barrier

; __device__ __forceinline__ unsigned xb_ld(unsigned* p)              { return __hip_atomic_load(p, __ATOMIC_RELAXED, __HIP_MEMORY_SCOPE_AGENT); }
; __device__ __forceinline__ void xcd_barrier_complete(unsigned* bar, unsigned x, unsigned& nloc, unsigned& nx) {
;     const unsigned G = gridDim.x * gridDim.y * gridDim.z;
;     unsigned sum, cnt, mine, sp = 0u;
;     for (;;) {
;         sum = 0u; cnt = 0u; mine = 0u;
; #pragma unroll
;         for (unsigned j = 0; j < 16; ++j) { const unsigned c = xb_ld(&bar[XB_XCNT(j)]); sum += c; cnt += (c > 0u) ? 1u : 0u; mine = (j == x) ? c : mine; }
; __device__ __forceinline__ void xcd_barrier(const XcdBarrier& b) {
;     asm volatile("s_waitcnt vmcnt(0)" ::: "memory");
;     __syncthreads();
;     if (threadIdx.x == 0) {
;         unsigned* bar = b.bar;
;         __builtin_amdgcn_s_waitcnt(0);
;         unsigned nloc = b.st[0], nx = b.st[1];
;         if (nloc == 0u) { xcd_barrier_complete(bar, b.x, nloc, nx); b.st[0] = nloc; b.st[1] = nx; }
.LBB0_690:
	v_readlane_b32 s0, v252, 30
	v_readlane_b32 s12, v253, 2
	s_add_i32 s21, s0, 6
	v_readlane_b32 s15, v253, 5
	s_cmp_ge_i32 s21, s15
	v_readlane_b32 s13, v253, 3
	v_readlane_b32 s14, v253, 4
	s_cbranch_scc1 .LBB0_744
	s_waitcnt vmcnt(0)
	s_waitcnt lgkmcnt(0)
	s_barrier
	s_setprio 0
	s_and_saveexec_b64 s[0:1], s[80:81]
	s_cbranch_execz .LBB0_743
	v_readlane_b32 s4, v254, 61
	s_waitcnt vmcnt(0) expcnt(0) lgkmcnt(0)
	s_nop 0
	v_mov_b32_e32 v2, s4
	ds_read_b32 v4, v2
	v_readlane_b32 s4, v254, 62
	s_waitcnt lgkmcnt(0)
	v_cmp_ne_u32_e32 vcc, 0, v4
	v_mov_b32_e32 v2, s4
	ds_read_b32 v2, v2
	s_cbranch_vccnz .LBB0_707
	v_readlane_b32 s12, v253, 6
	v_readlane_b32 s13, v253, 7
	s_load_dwordx2 s[4:5], s[12:13], 0x0
	s_nop 0
	s_load_dword s12, s[12:13], 0x8
	s_mov_b32 s17, 1
	s_waitcnt lgkmcnt(0)
	s_mul_i32 s16, s5, s4
	s_mul_i32 s16, s16, s12
	s_branch .LBB0_695

; #define PG8_STAGE(bufoff, gbase, voff) do { _Pragma("unroll") for (int _i = 0; _i < 2; ++_i) \
;         __builtin_amdgcn_global_load_lds((const unsigned*)((const char*)(gbase) + (voff)[_i]), (PG8_LAS unsigned*)(lds + (bufoff) + ldsw + _i * 8192), 16, 0, 0); } while (0)
; #define PG8_WAIT_V(n) asm volatile("s_waitcnt vmcnt(" #n ")" ::: "memory")
; #define PG8_BAR __builtin_amdgcn_s_barrier()
; template <class Epi, class Sched, bool ALIGN_EPI = false, bool SP2 = false>
; __device__ __forceinline__ void gemm_phase(PG8_LAS unsigned char* lds, const Gemm g, const Sched& S, const Epi& E) {
;     ...
;     for (int i = 0; i < 2; ++i) { int R, C; stage_rc(tid * 16 + i * 8192, R, C); const int Rb = Epi::PERM ? ((R & ~31) + perm32(R & 31)) : R;
;         voffA[i] = (unsigned)(R * K + C) * 2u; voffB[i] = (unsigned)(Rb * K + C) * 2u; }
;     const size_t kstep = (size_t)(BK * 2);
;     const size_t hstep = (size_t)HALF * K * 2;
;     const size_t tstep = 2 * hstep;
;     const unsigned ldsw = (unsigned)wid * 1024u;
;     const int aoff = lds_byte(wr * 64 + fr, fq * 8), boff = lds_byte(wc * 32 + fr, fq * 8);
;     ...
;         PG8_WAIT_V(2); PG8_BAR;
;         PG8_STAGE(PG8_SB(1, 0), cB + kstep, voffB); PG8_STAGE(PG8_SA(1, 0), cA + kstep, voffA); PG8_STAGE(PG8_SB(1, 1), cB + hstep + kstep, voffB);
;         PG8_WAIT_V(6); PG8_BAR;
.LBB0_752:
	v_lshrrev_b32_e32 v17, 1, v144
	v_and_b32_e32 v17, 24, v17
	v_and_b32_e32 v16, 15, v144
	v_lshlrev_b32_e32 v18, 1, v17
	s_add_u32 s14, s0, 0x25800000
	v_lshl_or_b32 v145, s18, 6, v16
	v_lshl_or_b32 v18, v16, 6, v18
	v_lshlrev_b32_e32 v16, 2, v16
	s_addc_u32 s15, s1, 0
	s_lshl_b32 s0, s18, 13
	v_and_b32_e32 v19, 32, v16
	v_bitop3_b32 v20, v18, s0, v19 bitop3:0xde
	s_lshl_b32 s0, s17, 5
	s_and_b32 s19, s0, 0x60
	s_add_i32 m0, s47, 0x18000
	v_lshl_add_u64 v[8:9], v[8:9], 0, s[10:11]
	s_lshl_b32 s0, s19, 7
	s_waitcnt vmcnt(2)
	s_barrier
	global_load_lds_dwordx4 v[8:9], off
	v_lshl_add_u64 v[6:7], v[6:7], 0, s[10:11]
	s_add_i32 m0, s47, 0x1a000
	s_add_i32 s52, s47, 0x8000
	s_add_i32 s53, s47, 0xa000
	v_bitop3_b32 v146, v18, s0, v19 bitop3:0xde
	global_load_lds_dwordx4 v[6:7], off
	v_lshl_add_u64 v[2:3], v[2:3], 0, s[10:11]
	s_mov_b32 m0, s52
	s_add_u32 s0, s30, 0x80080
	global_load_lds_dwordx4 v[2:3], off
	v_lshl_add_u64 v[2:3], v[4:5], 0, s[10:11]
	s_mov_b32 m0, s53
	s_addc_u32 s1, s31, 0
	global_load_lds_dwordx4 v[2:3], off
	s_add_i32 m0, s47, 0x1c000
	v_lshl_add_u64 v[2:3], s[0:1], 0, v[158:159]
	global_load_lds_dwordx4 v[2:3], off
	v_lshl_add_u64 v[2:3], s[0:1], 0, v[134:135]
	s_add_i32 m0, s47, 0x1e000
	s_cmpk_lt_u32 s16, 0x100
	global_load_lds_dwordx4 v[2:3], off
	v_lshlrev_b32_e32 v2, 15, v10
	v_and_b32_e32 v2, 0xffff0000, v2
	v_lshl_add_u32 v2, v11, 12, v2
	v_and_b32_e32 v3, 1, v10
	v_lshl_or_b32 v2, v3, 6, v2
	v_lshl_add_u32 v136, v12, 1, v2
	v_lshlrev_b32_e32 v2, 15, v13
	s_cselect_b64 s[16:17], -1, 0
	s_cbranch_scc1 .Lsp_3
	s_setprio 1
.Lsp_3:
	s_lshl_b32 s0, s18, 8
	s_add_i32 s1, 0, 0x20000
	v_and_b32_e32 v2, 0xffff0000, v2
	s_waitcnt vmcnt(6)
	s_add_i32 s0, s1, s0
	v_lshl_add_u32 v2, v14, 12, v2
	v_and_b32_e32 v3, 1, v13
	v_add_u32_e32 v147, s0, v16
	v_lshl_add_u32 v148, v144, 2, s1
	v_lshl_or_b32 v2, v3, 6, v2
	v_readlane_b32 s0, v252, 12
	s_waitcnt lgkmcnt(0)
	s_ashr_i32 s54, s51, 31
	v_or_b32_e32 v149, s19, v17
	v_mov_b32_e32 v137, v159
	v_lshl_add_u32 v138, v15, 1, v2
	v_mov_b32_e32 v139, v159
	s_mov_b32 s55, 0
	v_add_u32_e32 v150, 0, v20
	v_readlane_b32 s58, v254, 45
	s_mov_b32 s59, s0
	s_mov_b32 s57, s0
	s_mov_b32 s56, 0
	s_barrier
	v_readlane_b32 s1, v252, 13
	s_branch .LBB0_755

; #define PG8_STAGE(bufoff, gbase, voff) do { _Pragma("unroll") for (int _i = 0; _i < 2; ++_i) \
;         __builtin_amdgcn_global_load_lds((const unsigned*)((const char*)(gbase) + (voff)[_i]), (PG8_LAS unsigned*)(lds + (bufoff) + ldsw + _i * 8192), 16, 0, 0); } while (0)
; #define PG8_LDA(dst, b, h) do { _Pragma("unroll") for (int m = 0; m < 4; ++m) _Pragma("unroll") for (int k = 0; k < 2; ++k) dst[m][k] = *(const PG8_LAS bf16x8*)(lds + PG8_SA(b, h) + aoff + m * 2048 + k * 1024); } while (0)
; #define PG8_LDB(dst, b, h) do { _Pragma("unroll") for (int n = 0; n < 2; ++n) _Pragma("unroll") for (int k = 0; k < 2; ++k) dst[n][k] = *(const PG8_LAS bf16x8*)(lds + PG8_SB(b, h) + boff + n * 2048 + k * 1024); } while (0)
; #define PG8_MMA(ai, bj, At, Bt) do { __builtin_amdgcn_s_setprio(1); _Pragma("unroll") for (int m = 0; m < 4; ++m) _Pragma("unroll") for (int n = 0; n < 2; ++n) _Pragma("unroll") for (int k = 0; k < 2; ++k) \
;         acc[ai][bj][m][n] = __builtin_amdgcn_mfma_f32_16x16x32_bf16(Bt[n][k], At[m][k], acc[ai][bj][m][n], 0, 0, 0); __builtin_amdgcn_s_setprio(0); } while (0)
; #define PG8_WAIT_V(n) asm volatile("s_waitcnt vmcnt(" #n ")" ::: "memory")
; #define PG8_BAR __builtin_amdgcn_s_barrier()
; template <class Epi, class Sched, bool ALIGN_EPI = false, bool SP2 = false>
; __device__ __forceinline__ void gemm_phase(PG8_LAS unsigned char* lds, const Gemm g, const Sched& S, const Epi& E) {
;     ...
;         for (int t = 0; t < nt; t += 2) {
;             const bool last = (t == nt - 2);
;             const char* a1 = cA + (size_t)(t + 1) * kstep;
;             const char* a2 = last ? nA : cA + (size_t)(t + 2) * kstep; const char* b2 = last ? nB : cB + (size_t)(t + 2) * kstep;
;             const char* a3 = a2 + kstep; const char* b3 = b2 + kstep;
;             if (last && has_next) S.a_ready(nxt);
;             if constexpr (SP2) {
;             PG8_LDB(B0, 0, 0); PG8_LDB(B1, 0, 1); PG8_SCHED; PG8_LDA(At, 0, 0); PG8_STAGE(PG8_SA(1, 1), a1 + hstep, voffA);
;             PG8_WAIT_V(8); PG8_WAIT_L(0); PG8_BAR; PG8_MMA(0, 0, At, B0); PG8_MMA(0, 1, At, B1); PG8_BAR; PG8_SCHED;
;             PG8_LDA(At, 0, 1); PG8_STAGE(PG8_SB(0, 0), b2, voffB); PG8_STAGE(PG8_SB(0, 1), b2 + hstep, voffB); PG8_STAGE(PG8_SA(0, 0), a2, voffA);
;             PG8_WAIT_V(8); PG8_WAIT_L(0); PG8_BAR; PG8_MMA(1, 0, At, B0); PG8_MMA(1, 1, At, B1); PG8_BAR; PG8_SCHED;
.LBB0_762:
	s_add_u32 s30, s0, 0xfff80080
	s_addc_u32 s31, s1, -1
	s_add_i32 s67, 0, 0x10000
	s_cmp_eq_u32 s66, 28
	s_cselect_b32 s37, s23, s31
	s_cselect_b32 s36, s60, s30
	v_add_u32_e32 v151, s67, v146
	s_cselect_b32 s31, s19, s63
	s_cselect_b32 s30, s61, s62
	s_add_i32 s70, 0, 0x14000
	ds_read_b128 v[140:143], v151
	ds_read_b128 v[152:155], v151 offset:1024
	ds_read_b128 v[162:165], v151 offset:2048
	ds_read_b128 v[166:169], v151 offset:3072
	v_add_u32_e32 v151, s70, v146
	ds_read_b128 v[170:173], v151
	ds_read_b128 v[174:177], v151 offset:1024
	ds_read_b128 v[178:181], v151 offset:2048
	ds_read_b128 v[182:185], v151 offset:3072
	s_add_u32 s98, s0, 0xfff80000
	s_addc_u32 s99, s1, -1
	s_mov_b32 m0, s52
	s_nop 0
	global_load_lds_dwordx4 v136, s[98:99]
	s_mov_b32 m0, s53
	s_nop 0
	global_load_lds_dwordx4 v138, s[98:99]
	s_add_i32 m0, s47, 0xc000
	ds_read_b128 v[186:189], v150
	ds_read_b128 v[190:193], v150 offset:1024
	ds_read_b128 v[200:203], v150 offset:2048
	ds_read_b128 v[204:207], v150 offset:3072
	ds_read_b128 v[208:211], v150 offset:4096
	ds_read_b128 v[212:215], v150 offset:5120
	ds_read_b128 v[216:219], v150 offset:6144
	ds_read_b128 v[220:223], v150 offset:7168
	global_load_lds_dwordx4 v136, s[0:1]
	s_add_i32 m0, s47, 0xe000
	s_nop 0
	global_load_lds_dwordx4 v138, s[0:1]
	s_waitcnt vmcnt(8)
	s_waitcnt lgkmcnt(0)
	s_barrier
	s_waitcnt lgkmcnt(0)
	v_mfma_f32_16x16x32_bf16 v[126:129], v[140:143], v[186:189], v[126:129]
	v_mfma_f32_16x16x32_bf16 v[122:125], v[162:165], v[186:189], v[122:125]
	v_mfma_f32_16x16x32_bf16 v[110:113], v[140:143], v[200:203], v[110:113]
	v_mfma_f32_16x16x32_bf16 v[106:109], v[162:165], v[200:203], v[106:109]
	v_mfma_f32_16x16x32_bf16 v[94:97], v[140:143], v[208:211], v[94:97]
	v_mfma_f32_16x16x32_bf16 v[90:93], v[162:165], v[208:211], v[90:93]
	v_mfma_f32_16x16x32_bf16 v[78:81], v[140:143], v[216:219], v[78:81]
	v_mfma_f32_16x16x32_bf16 v[74:77], v[162:165], v[216:219], v[74:77]
	v_mfma_f32_16x16x32_bf16 v[126:129], v[152:155], v[190:193], v[126:129]
	v_mfma_f32_16x16x32_bf16 v[122:125], v[166:169], v[190:193], v[122:125]
	v_mfma_f32_16x16x32_bf16 v[110:113], v[152:155], v[204:207], v[110:113]
	v_mfma_f32_16x16x32_bf16 v[106:109], v[166:169], v[204:207], v[106:109]
	v_mfma_f32_16x16x32_bf16 v[94:97], v[152:155], v[212:215], v[94:97]
	v_mfma_f32_16x16x32_bf16 v[90:93], v[166:169], v[212:215], v[90:93]
	v_mfma_f32_16x16x32_bf16 v[78:81], v[152:155], v[220:223], v[78:81]
	v_mfma_f32_16x16x32_bf16 v[74:77], v[166:169], v[220:223], v[74:77]
	v_mfma_f32_16x16x32_bf16 v[118:121], v[170:173], v[186:189], v[118:121]
	v_mfma_f32_16x16x32_bf16 v[114:117], v[178:181], v[186:189], v[114:117]
	v_mfma_f32_16x16x32_bf16 v[102:105], v[170:173], v[200:203], v[102:105]
	v_mfma_f32_16x16x32_bf16 v[98:101], v[178:181], v[200:203], v[98:101]
	v_mfma_f32_16x16x32_bf16 v[86:89], v[170:173], v[208:211], v[86:89]
	v_mfma_f32_16x16x32_bf16 v[82:85], v[178:181], v[208:211], v[82:85]
	v_mfma_f32_16x16x32_bf16 v[70:73], v[170:173], v[216:219], v[70:73]
	v_mfma_f32_16x16x32_bf16 v[66:69], v[178:181], v[216:219], v[66:69]
	v_mfma_f32_16x16x32_bf16 v[118:121], v[174:177], v[190:193], v[118:121]
	v_mfma_f32_16x16x32_bf16 v[114:117], v[182:185], v[190:193], v[114:117]
	v_mfma_f32_16x16x32_bf16 v[102:105], v[174:177], v[204:207], v[102:105]
	v_mfma_f32_16x16x32_bf16 v[98:101], v[182:185], v[204:207], v[98:101]
	v_mfma_f32_16x16x32_bf16 v[86:89], v[174:177], v[212:215], v[86:89]
	v_mfma_f32_16x16x32_bf16 v[82:85], v[182:185], v[212:215], v[82:85]
	v_mfma_f32_16x16x32_bf16 v[70:73], v[174:177], v[220:223], v[70:73]
	v_mfma_f32_16x16x32_bf16 v[66:69], v[182:185], v[220:223], v[66:69]
	s_barrier
	s_add_i32 s67, s67, s46
	s_mov_b32 m0, s67
	ds_read_b128 v[186:189], v150 offset:16384
	ds_read_b128 v[190:193], v150 offset:17408
	ds_read_b128 v[200:203], v150 offset:18432
	ds_read_b128 v[204:207], v150 offset:19456
	ds_read_b128 v[208:211], v150 offset:20480
	ds_read_b128 v[212:215], v150 offset:21504
	ds_read_b128 v[216:219], v150 offset:22528
	ds_read_b128 v[220:223], v150 offset:23552
	global_load_lds_dwordx4 v158, s[30:31]
	s_add_i32 m0, s67, 0x2000
	s_add_u32 s68, s30, 0x80000
	s_addc_u32 s69, s31, 0
	s_add_i32 s67, s70, s46
	global_load_lds_dwordx4 v134, s[30:31]
	s_mov_b32 m0, s67
	s_nop 0
	global_load_lds_dwordx4 v158, s[68:69]
	s_add_i32 m0, s67, 0x2000
	s_nop 0
	global_load_lds_dwordx4 v134, s[68:69]
	s_waitcnt vmcnt(6)
	s_waitcnt lgkmcnt(0)
	s_barrier
	s_waitcnt lgkmcnt(0)
	v_mfma_f32_16x16x32_bf16 v[62:65], v[140:143], v[186:189], v[62:65]
	v_mfma_f32_16x16x32_bf16 v[58:61], v[162:165], v[186:189], v[58:61]
	v_mfma_f32_16x16x32_bf16 v[46:49], v[140:143], v[200:203], v[46:49]
	v_mfma_f32_16x16x32_bf16 v[42:45], v[162:165], v[200:203], v[42:45]
	v_mfma_f32_16x16x32_bf16 v[30:33], v[140:143], v[208:211], v[30:33]
	v_mfma_f32_16x16x32_bf16 v[26:29], v[162:165], v[208:211], v[26:29]
	v_mfma_f32_16x16x32_bf16 v[14:17], v[140:143], v[216:219], v[14:17]
	v_mfma_f32_16x16x32_bf16 v[10:13], v[162:165], v[216:219], v[10:13]
	v_mfma_f32_16x16x32_bf16 v[62:65], v[152:155], v[190:193], v[62:65]
	v_mfma_f32_16x16x32_bf16 v[58:61], v[166:169], v[190:193], v[58:61]
	v_mfma_f32_16x16x32_bf16 v[46:49], v[152:155], v[204:207], v[46:49]
	v_mfma_f32_16x16x32_bf16 v[42:45], v[166:169], v[204:207], v[42:45]
	v_mfma_f32_16x16x32_bf16 v[30:33], v[152:155], v[212:215], v[30:33]
	v_mfma_f32_16x16x32_bf16 v[26:29], v[166:169], v[212:215], v[26:29]
	v_mfma_f32_16x16x32_bf16 v[14:17], v[152:155], v[220:223], v[14:17]
	v_mfma_f32_16x16x32_bf16 v[10:13], v[166:169], v[220:223], v[10:13]
	v_mfma_f32_16x16x32_bf16 v[54:57], v[170:173], v[186:189], v[54:57]
	v_mfma_f32_16x16x32_bf16 v[50:53], v[178:181], v[186:189], v[50:53]
	v_mfma_f32_16x16x32_bf16 v[38:41], v[170:173], v[200:203], v[38:41]
	v_mfma_f32_16x16x32_bf16 v[34:37], v[178:181], v[200:203], v[34:37]
	v_mfma_f32_16x16x32_bf16 v[22:25], v[170:173], v[208:211], v[22:25]
	v_mfma_f32_16x16x32_bf16 v[18:21], v[178:181], v[208:211], v[18:21]
	v_mfma_f32_16x16x32_bf16 v[6:9], v[170:173], v[216:219], v[6:9]
	v_mfma_f32_16x16x32_bf16 v[2:5], v[178:181], v[216:219], v[2:5]
	v_mfma_f32_16x16x32_bf16 v[54:57], v[174:177], v[190:193], v[54:57]
	v_mfma_f32_16x16x32_bf16 v[50:53], v[182:185], v[190:193], v[50:53]
	v_mfma_f32_16x16x32_bf16 v[38:41], v[174:177], v[204:207], v[38:41]
	v_mfma_f32_16x16x32_bf16 v[34:37], v[182:185], v[204:207], v[34:37]
	v_mfma_f32_16x16x32_bf16 v[22:25], v[174:177], v[212:215], v[22:25]
	v_mfma_f32_16x16x32_bf16 v[18:21], v[182:185], v[212:215], v[18:21]
	v_mfma_f32_16x16x32_bf16 v[6:9], v[174:177], v[220:223], v[6:9]
	v_mfma_f32_16x16x32_bf16 v[2:5], v[182:185], v[220:223], v[2:5]
	s_barrier
; #define PG8_STAGE(bufoff, gbase, voff) do { _Pragma("unroll") for (int _i = 0; _i < 2; ++_i) \
;         __builtin_amdgcn_global_load_lds((const unsigned*)((const char*)(gbase) + (voff)[_i]), (PG8_LAS unsigned*)(lds + (bufoff) + ldsw + _i * 8192), 16, 0, 0); } while (0)
; #define PG8_LDA(dst, b, h) do { _Pragma("unroll") for (int m = 0; m < 4; ++m) _Pragma("unroll") for (int k = 0; k < 2; ++k) dst[m][k] = *(const PG8_LAS bf16x8*)(lds + PG8_SA(b, h) + aoff + m * 2048 + k * 1024); } while (0)
; #define PG8_LDB(dst, b, h) do { _Pragma("unroll") for (int n = 0; n < 2; ++n) _Pragma("unroll") for (int k = 0; k < 2; ++k) dst[n][k] = *(const PG8_LAS bf16x8*)(lds + PG8_SB(b, h) + boff + n * 2048 + k * 1024); } while (0)
; #define PG8_MMA(ai, bj, At, Bt) do { __builtin_amdgcn_s_setprio(1); _Pragma("unroll") for (int m = 0; m < 4; ++m) _Pragma("unroll") for (int n = 0; n < 2; ++n) _Pragma("unroll") for (int k = 0; k < 2; ++k) \
;         acc[ai][bj][m][n] = __builtin_amdgcn_mfma_f32_16x16x32_bf16(Bt[n][k], At[m][k], acc[ai][bj][m][n], 0, 0, 0); __builtin_amdgcn_s_setprio(0); } while (0)
; #define PG8_WAIT_V(n) asm volatile("s_waitcnt vmcnt(" #n ")" ::: "memory")
; #define PG8_WAIT_L(n) asm volatile("s_waitcnt lgkmcnt(" #n ")" ::: "memory")
; #define PG8_BAR __builtin_amdgcn_s_barrier()
; #define PG8_SCHED __builtin_amdgcn_sched_barrier(0)
; template <class Epi, class Sched, bool ALIGN_EPI = false, bool SP2 = false>
; __device__ __forceinline__ void gemm_phase(PG8_LAS unsigned char* lds, const Gemm g, const Sched& S, const Epi& E) {
;     ...
;             PG8_LDB(B0, 1, 0); PG8_LDB(B1, 1, 1); PG8_SCHED; PG8_LDA(At, 1, 0); PG8_STAGE(PG8_SA(0, 1), a2 + hstep, voffA);
;             PG8_WAIT_V(8); PG8_WAIT_L(0); PG8_BAR; PG8_MMA(0, 0, At, B0); PG8_MMA(0, 1, At, B1); PG8_BAR; PG8_SCHED;
;             PG8_LDA(At, 1, 1); PG8_STAGE(PG8_SB(1, 0), b3, voffB); PG8_STAGE(PG8_SB(1, 1), b3 + hstep, voffB); PG8_STAGE(PG8_SA(1, 0), a3, voffA);
;             PG8_WAIT_V(8); PG8_WAIT_L(0); PG8_BAR; PG8_MMA(1, 0, At, B0); PG8_MMA(1, 1, At, B1); PG8_BAR; PG8_SCHED;
;     ...
;         if constexpr (ALIGN_EPI) { if (wr == 0) PG8_BAR; }
	s_add_i32 s67, 0, 0x18000
	v_add_u32_e32 v151, s67, v146
	s_add_i32 s68, 0, 0x1c000
	ds_read_b128 v[140:143], v151
	ds_read_b128 v[152:155], v151 offset:1024
	ds_read_b128 v[162:165], v151 offset:2048
	ds_read_b128 v[166:169], v151 offset:3072
	v_add_u32_e32 v151, s68, v146
	ds_read_b128 v[170:173], v151
	ds_read_b128 v[174:177], v151 offset:1024
	ds_read_b128 v[178:181], v151 offset:2048
	ds_read_b128 v[182:185], v151 offset:3072
	s_mov_b32 m0, s47
	s_nop 0
	global_load_lds_dwordx4 v130, s[36:37]
	s_mov_b32 m0, s48
	s_nop 0
	global_load_lds_dwordx4 v132, s[36:37]
	s_add_u32 s36, s36, 0x80000
	s_addc_u32 s37, s37, 0
	s_mov_b32 m0, s49
	ds_read_b128 v[186:189], v150 offset:32768
	ds_read_b128 v[190:193], v150 offset:33792
	ds_read_b128 v[200:203], v150 offset:34816
	ds_read_b128 v[204:207], v150 offset:35840
	ds_read_b128 v[208:211], v150 offset:36864
	ds_read_b128 v[212:215], v150 offset:37888
	ds_read_b128 v[216:219], v150 offset:38912
	ds_read_b128 v[220:223], v150 offset:39936
	global_load_lds_dwordx4 v130, s[36:37]
	s_mov_b32 m0, s50
	s_nop 0
	global_load_lds_dwordx4 v132, s[36:37]
	s_waitcnt vmcnt(8)
	s_waitcnt lgkmcnt(0)
	s_barrier
	s_waitcnt lgkmcnt(0)
	v_mfma_f32_16x16x32_bf16 v[126:129], v[140:143], v[186:189], v[126:129]
	v_mfma_f32_16x16x32_bf16 v[122:125], v[162:165], v[186:189], v[122:125]
	v_mfma_f32_16x16x32_bf16 v[110:113], v[140:143], v[200:203], v[110:113]
	v_mfma_f32_16x16x32_bf16 v[106:109], v[162:165], v[200:203], v[106:109]
	v_mfma_f32_16x16x32_bf16 v[94:97], v[140:143], v[208:211], v[94:97]
	v_mfma_f32_16x16x32_bf16 v[90:93], v[162:165], v[208:211], v[90:93]
	v_mfma_f32_16x16x32_bf16 v[78:81], v[140:143], v[216:219], v[78:81]
	v_mfma_f32_16x16x32_bf16 v[74:77], v[162:165], v[216:219], v[74:77]
	v_mfma_f32_16x16x32_bf16 v[126:129], v[152:155], v[190:193], v[126:129]
	v_mfma_f32_16x16x32_bf16 v[122:125], v[166:169], v[190:193], v[122:125]
	v_mfma_f32_16x16x32_bf16 v[110:113], v[152:155], v[204:207], v[110:113]
	v_mfma_f32_16x16x32_bf16 v[106:109], v[166:169], v[204:207], v[106:109]
	v_mfma_f32_16x16x32_bf16 v[94:97], v[152:155], v[212:215], v[94:97]
	v_mfma_f32_16x16x32_bf16 v[90:93], v[166:169], v[212:215], v[90:93]
	v_mfma_f32_16x16x32_bf16 v[78:81], v[152:155], v[220:223], v[78:81]
	v_mfma_f32_16x16x32_bf16 v[74:77], v[166:169], v[220:223], v[74:77]
	v_mfma_f32_16x16x32_bf16 v[118:121], v[170:173], v[186:189], v[118:121]
	v_mfma_f32_16x16x32_bf16 v[114:117], v[178:181], v[186:189], v[114:117]
	v_mfma_f32_16x16x32_bf16 v[102:105], v[170:173], v[200:203], v[102:105]
	v_mfma_f32_16x16x32_bf16 v[98:101], v[178:181], v[200:203], v[98:101]
	v_mfma_f32_16x16x32_bf16 v[86:89], v[170:173], v[208:211], v[86:89]
	v_mfma_f32_16x16x32_bf16 v[82:85], v[178:181], v[208:211], v[82:85]
	v_mfma_f32_16x16x32_bf16 v[70:73], v[170:173], v[216:219], v[70:73]
	v_mfma_f32_16x16x32_bf16 v[66:69], v[178:181], v[216:219], v[66:69]
	v_mfma_f32_16x16x32_bf16 v[118:121], v[174:177], v[190:193], v[118:121]
	v_mfma_f32_16x16x32_bf16 v[114:117], v[182:185], v[190:193], v[114:117]
	v_mfma_f32_16x16x32_bf16 v[102:105], v[174:177], v[204:207], v[102:105]
	v_mfma_f32_16x16x32_bf16 v[98:101], v[182:185], v[204:207], v[98:101]
	v_mfma_f32_16x16x32_bf16 v[86:89], v[174:177], v[212:215], v[86:89]
	v_mfma_f32_16x16x32_bf16 v[82:85], v[182:185], v[212:215], v[82:85]
	v_mfma_f32_16x16x32_bf16 v[70:73], v[174:177], v[220:223], v[70:73]
	v_mfma_f32_16x16x32_bf16 v[66:69], v[182:185], v[220:223], v[66:69]
	s_barrier
	s_add_i32 s36, s67, s46
	s_add_i32 m0, s36, 0xffffff80
	ds_read_b128 v[186:189], v150 offset:49152
	ds_read_b128 v[190:193], v150 offset:50176
	ds_read_b128 v[200:203], v150 offset:51200
	ds_read_b128 v[204:207], v150 offset:52224
	ds_read_b128 v[208:211], v150 offset:53248
	ds_read_b128 v[212:215], v150 offset:54272
	ds_read_b128 v[216:219], v150 offset:55296
	ds_read_b128 v[220:223], v150 offset:56320
	global_load_lds_dwordx4 v158, s[30:31] offset:128
	s_add_i32 m0, s36, 0x1f80
	s_add_i32 s36, s68, s46
	global_load_lds_dwordx4 v134, s[30:31] offset:128
	s_add_u32 s30, s30, 0x80080
	s_addc_u32 s31, s31, 0
	s_mov_b32 m0, s36
	s_nop 0
	global_load_lds_dwordx4 v158, s[30:31]
	s_add_i32 m0, s36, 0x2000
	s_nop 0
	global_load_lds_dwordx4 v134, s[30:31]
	s_waitcnt vmcnt(6)
	s_waitcnt lgkmcnt(0)
	s_barrier
	s_waitcnt lgkmcnt(0)
	v_mfma_f32_16x16x32_bf16 v[62:65], v[140:143], v[186:189], v[62:65]
	v_mfma_f32_16x16x32_bf16 v[58:61], v[162:165], v[186:189], v[58:61]
	v_mfma_f32_16x16x32_bf16 v[46:49], v[140:143], v[200:203], v[46:49]
	v_mfma_f32_16x16x32_bf16 v[42:45], v[162:165], v[200:203], v[42:45]
	v_mfma_f32_16x16x32_bf16 v[30:33], v[140:143], v[208:211], v[30:33]
	v_mfma_f32_16x16x32_bf16 v[26:29], v[162:165], v[208:211], v[26:29]
	v_mfma_f32_16x16x32_bf16 v[14:17], v[140:143], v[216:219], v[14:17]
	v_mfma_f32_16x16x32_bf16 v[10:13], v[162:165], v[216:219], v[10:13]
	v_mfma_f32_16x16x32_bf16 v[62:65], v[152:155], v[190:193], v[62:65]
	v_mfma_f32_16x16x32_bf16 v[58:61], v[166:169], v[190:193], v[58:61]
	v_mfma_f32_16x16x32_bf16 v[46:49], v[152:155], v[204:207], v[46:49]
	v_mfma_f32_16x16x32_bf16 v[42:45], v[166:169], v[204:207], v[42:45]
	v_mfma_f32_16x16x32_bf16 v[30:33], v[152:155], v[212:215], v[30:33]
	v_mfma_f32_16x16x32_bf16 v[26:29], v[166:169], v[212:215], v[26:29]
	v_mfma_f32_16x16x32_bf16 v[14:17], v[152:155], v[220:223], v[14:17]
	v_mfma_f32_16x16x32_bf16 v[10:13], v[166:169], v[220:223], v[10:13]
	v_mfma_f32_16x16x32_bf16 v[54:57], v[170:173], v[186:189], v[54:57]
	v_mfma_f32_16x16x32_bf16 v[50:53], v[178:181], v[186:189], v[50:53]
	v_mfma_f32_16x16x32_bf16 v[38:41], v[170:173], v[200:203], v[38:41]
	v_mfma_f32_16x16x32_bf16 v[34:37], v[178:181], v[200:203], v[34:37]
	v_mfma_f32_16x16x32_bf16 v[22:25], v[170:173], v[208:211], v[22:25]
	v_mfma_f32_16x16x32_bf16 v[18:21], v[178:181], v[208:211], v[18:21]
	v_mfma_f32_16x16x32_bf16 v[6:9], v[170:173], v[216:219], v[6:9]
	v_mfma_f32_16x16x32_bf16 v[2:5], v[178:181], v[216:219], v[2:5]
	v_mfma_f32_16x16x32_bf16 v[54:57], v[174:177], v[190:193], v[54:57]
	v_mfma_f32_16x16x32_bf16 v[50:53], v[182:185], v[190:193], v[50:53]
	v_mfma_f32_16x16x32_bf16 v[38:41], v[174:177], v[204:207], v[38:41]
	v_mfma_f32_16x16x32_bf16 v[34:37], v[182:185], v[204:207], v[34:37]
	v_mfma_f32_16x16x32_bf16 v[22:25], v[174:177], v[212:215], v[22:25]
	v_mfma_f32_16x16x32_bf16 v[18:21], v[182:185], v[212:215], v[18:21]
	v_mfma_f32_16x16x32_bf16 v[6:9], v[174:177], v[220:223], v[6:9]
	v_mfma_f32_16x16x32_bf16 v[2:5], v[182:185], v[220:223], v[2:5]
	s_barrier
	s_add_i32 s66, s66, 2
	s_add_u32 s0, s0, 0x100
	s_addc_u32 s1, s1, 0
	s_add_u32 s62, s62, 0x100
	s_addc_u32 s63, s63, 0
	s_cmp_gt_u32 s66, 29
	s_cbranch_scc0 .LBB0_762
	s_and_b64 vcc, exec, s[16:17]
	s_mov_b64 s[60:61], s[90:91]
	s_mov_b64 s[62:63], s[88:89]
	s_cbranch_vccz .LBB0_765
	s_barrier

; __device__ __forceinline__ unsigned xb_ld(unsigned* p)              { return __hip_atomic_load(p, __ATOMIC_RELAXED, __HIP_MEMORY_SCOPE_AGENT); }
; __device__ __forceinline__ void xcd_barrier_complete(unsigned* bar, unsigned x, unsigned& nloc, unsigned& nx) {
;     const unsigned G = gridDim.x * gridDim.y * gridDim.z;
;     unsigned sum, cnt, mine, sp = 0u;
;     for (;;) {
;         sum = 0u; cnt = 0u; mine = 0u;
; #pragma unroll
;         for (unsigned j = 0; j < 16; ++j) { const unsigned c = xb_ld(&bar[XB_XCNT(j)]); sum += c; cnt += (c > 0u) ? 1u : 0u; mine = (j == x) ? c : mine; }
; __device__ __forceinline__ void xcd_barrier(const XcdBarrier& b) {
;     asm volatile("s_waitcnt vmcnt(0)" ::: "memory");
;     __syncthreads();
;     if (threadIdx.x == 0) {
;         unsigned* bar = b.bar;
;         __builtin_amdgcn_s_waitcnt(0);
;         unsigned nloc = b.st[0], nx = b.st[1];
;         if (nloc == 0u) { xcd_barrier_complete(bar, b.x, nloc, nx); b.st[0] = nloc; b.st[1] = nx; }
.LBB0_773:
	v_readlane_b32 s0, v252, 30
	v_readlane_b32 s12, v253, 2
	s_add_i32 s21, s0, 7
	v_readlane_b32 s15, v253, 5
	s_cmp_ge_i32 s21, s15
	v_readlane_b32 s13, v253, 3
	v_readlane_b32 s14, v253, 4
	s_cbranch_scc1 .LBB0_827
	s_waitcnt vmcnt(0)
	s_waitcnt vmcnt(0) lgkmcnt(0)
	s_barrier
	s_setprio 0
	s_and_saveexec_b64 s[0:1], s[80:81]
	s_cbranch_execz .LBB0_826
	v_readlane_b32 s4, v254, 61
	s_waitcnt vmcnt(0) expcnt(0) lgkmcnt(0)
	s_nop 0
	v_mov_b32_e32 v2, s4
	ds_read_b32 v4, v2
	v_readlane_b32 s4, v254, 62
	s_waitcnt lgkmcnt(0)
	v_cmp_ne_u32_e32 vcc, 0, v4
	v_mov_b32_e32 v2, s4
	ds_read_b32 v2, v2
	s_cbranch_vccnz .LBB0_790
	v_readlane_b32 s12, v253, 6
	v_readlane_b32 s13, v253, 7
	s_load_dwordx2 s[4:5], s[12:13], 0x0
	s_nop 0
	s_load_dword s12, s[12:13], 0x8
	s_mov_b32 s17, 1
	s_waitcnt lgkmcnt(0)
	s_mul_i32 s16, s5, s4
	s_mul_i32 s16, s16, s12
	s_branch .LBB0_778

; #define PG8_STAGE(bufoff, gbase, voff) do { _Pragma("unroll") for (int _i = 0; _i < 2; ++_i) \
;         __builtin_amdgcn_global_load_lds((const unsigned*)((const char*)(gbase) + (voff)[_i]), (PG8_LAS unsigned*)(lds + (bufoff) + ldsw + _i * 8192), 16, 0, 0); } while (0)
; #define PG8_WAIT_V(n) asm volatile("s_waitcnt vmcnt(" #n ")" ::: "memory")
; #define PG8_BAR __builtin_amdgcn_s_barrier()
; template <class Epi, class Sched, bool ALIGN_EPI = false, bool SP2 = false>
; __device__ __forceinline__ void gemm_phase(PG8_LAS unsigned char* lds, const Gemm g, const Sched& S, const Epi& E) {
;     ...
;     for (int i = 0; i < 2; ++i) { int R, C; stage_rc(tid * 16 + i * 8192, R, C); const int Rb = Epi::PERM ? ((R & ~31) + perm32(R & 31)) : R;
;         voffA[i] = (unsigned)(R * K + C) * 2u; voffB[i] = (unsigned)(Rb * K + C) * 2u; }
;     const size_t kstep = (size_t)(BK * 2);
;     const size_t hstep = (size_t)HALF * K * 2;
;     const size_t tstep = 2 * hstep;
;     const unsigned ldsw = (unsigned)wid * 1024u;
;     const int aoff = lds_byte(wr * 64 + fr, fq * 8), boff = lds_byte(wc * 32 + fr, fq * 8);
;     ...
;         PG8_WAIT_V(2); PG8_BAR;
;         PG8_STAGE(PG8_SB(1, 0), cB + kstep, voffB); PG8_STAGE(PG8_SA(1, 0), cA + kstep, voffA); PG8_STAGE(PG8_SB(1, 1), cB + hstep + kstep, voffB);
;         PG8_WAIT_V(6); PG8_BAR;
.LBB0_832:
	v_bfe_u32 v17, v16, 4, 2
	s_add_u32 s14, s14, 0xa00000
	v_and_b32_e32 v18, 15, v16
	v_lshlrev_b32_e32 v20, 4, v17
	v_lshlrev_b32_e32 v16, 2, v16
	s_addc_u32 s15, s15, 0
	s_and_b32 s55, s18, 3
	v_lshl_or_b32 v161, s17, 6, v18
	v_lshl_or_b32 v18, v18, 6, v20
	s_lshl_b32 s17, s17, 13
	v_and_b32_e32 v16, 32, v16
	s_add_i32 m0, s51, 0x18000
	v_lshl_add_u64 v[8:9], v[8:9], 0, s[10:11]
	v_bitop3_b32 v20, v18, s17, v16 bitop3:0xde
	s_lshl_b32 s17, s55, 12
	s_waitcnt vmcnt(2)
	s_barrier
	global_load_lds_dwordx4 v[8:9], off
	v_lshl_add_u64 v[6:7], v[6:7], 0, s[10:11]
	s_add_i32 m0, s51, 0x1a000
	s_add_i32 s56, s51, 0x8000
	s_add_i32 s57, s51, 0xa000
	global_load_lds_dwordx4 v[6:7], off
	v_lshl_add_u64 v[2:3], v[2:3], 0, s[10:11]
	s_mov_b32 m0, s56
	s_add_u32 s18, s30, 0x200080
	global_load_lds_dwordx4 v[2:3], off
	v_lshl_add_u64 v[2:3], v[4:5], 0, s[10:11]
	s_mov_b32 m0, s57
	s_addc_u32 s19, s31, 0
	global_load_lds_dwordx4 v[2:3], off
	s_add_i32 m0, s51, 0x1c000
	v_lshl_add_u64 v[2:3], s[18:19], 0, v[158:159]
	global_load_lds_dwordx4 v[2:3], off
	v_lshl_add_u64 v[2:3], s[18:19], 0, v[166:167]
	s_add_i32 m0, s51, 0x1e000
	v_lshlrev_b32_e32 v19, 3, v17
	global_load_lds_dwordx4 v[2:3], off
	v_lshlrev_b32_e32 v2, 17, v14
	v_and_b32_e32 v2, 0xfffc0000, v2
	v_lshl_add_u32 v2, v13, 14, v2
	v_and_b32_e32 v3, 1, v14
	v_lshl_or_b32 v2, v3, 6, v2
	v_lshl_add_u32 v172, v15, 1, v2
	v_lshlrev_b32_e32 v2, 17, v10
	v_and_b32_e32 v2, 0xfffc0000, v2
	s_waitcnt vmcnt(6)
	v_lshl_add_u32 v2, v11, 14, v2
	v_and_b32_e32 v3, 1, v10
	s_cmpk_lt_u32 s16, 0x100
	v_lshl_or_b32 v2, v3, 6, v2
	v_readlane_b32 s18, v252, 22
	v_bitop3_b32 v199, v18, s17, v16 bitop3:0xde
	v_lshl_or_b32 v200, s55, 5, v19
	s_cselect_b64 s[16:17], -1, 0
	s_cbranch_scc1 .Lsp_4
	s_setprio 1
.Lsp_4:
	s_mov_b32 s58, 0
	v_cmp_eq_u32_e64 s[42:43], 0, v17
	s_ashr_i32 s59, s21, 31
	v_mov_b32_e32 v173, v159
	v_lshl_add_u32 v174, v12, 1, v2
	v_mov_b32_e32 v175, v159
	v_add_u32_e32 v201, 0, v20
	v_readlane_b32 s34, v254, 48
	s_mov_b32 s60, s18
	s_barrier
	v_readlane_b32 s19, v252, 23
	s_branch .LBB0_835

; #define PG8_STAGE(bufoff, gbase, voff) do { _Pragma("unroll") for (int _i = 0; _i < 2; ++_i) \
;         __builtin_amdgcn_global_load_lds((const unsigned*)((const char*)(gbase) + (voff)[_i]), (PG8_LAS unsigned*)(lds + (bufoff) + ldsw + _i * 8192), 16, 0, 0); } while (0)
; #define PG8_LDA(dst, b, h) do { _Pragma("unroll") for (int m = 0; m < 4; ++m) _Pragma("unroll") for (int k = 0; k < 2; ++k) dst[m][k] = *(const PG8_LAS bf16x8*)(lds + PG8_SA(b, h) + aoff + m * 2048 + k * 1024); } while (0)
; #define PG8_LDB(dst, b, h) do { _Pragma("unroll") for (int n = 0; n < 2; ++n) _Pragma("unroll") for (int k = 0; k < 2; ++k) dst[n][k] = *(const PG8_LAS bf16x8*)(lds + PG8_SB(b, h) + boff + n * 2048 + k * 1024); } while (0)
; #define PG8_MMA(ai, bj, At, Bt) do { __builtin_amdgcn_s_setprio(1); _Pragma("unroll") for (int m = 0; m < 4; ++m) _Pragma("unroll") for (int n = 0; n < 2; ++n) _Pragma("unroll") for (int k = 0; k < 2; ++k) \
;         acc[ai][bj][m][n] = __builtin_amdgcn_mfma_f32_16x16x32_bf16(Bt[n][k], At[m][k], acc[ai][bj][m][n], 0, 0, 0); __builtin_amdgcn_s_setprio(0); } while (0)
; #define PG8_WAIT_V(n) asm volatile("s_waitcnt vmcnt(" #n ")" ::: "memory")
; #define PG8_BAR __builtin_amdgcn_s_barrier()
; template <class Epi, class Sched, bool ALIGN_EPI = false, bool SP2 = false>
; __device__ __forceinline__ void gemm_phase(PG8_LAS unsigned char* lds, const Gemm g, const Sched& S, const Epi& E) {
;     ...
;         for (int t = 0; t < nt; t += 2) {
;             const bool last = (t == nt - 2);
;             const char* a1 = cA + (size_t)(t + 1) * kstep;
;             const char* a2 = last ? nA : cA + (size_t)(t + 2) * kstep; const char* b2 = last ? nB : cB + (size_t)(t + 2) * kstep;
;             const char* a3 = a2 + kstep; const char* b3 = b2 + kstep;
;             if (last && has_next) S.a_ready(nxt);
;             if constexpr (SP2) {
;             PG8_LDB(B0, 0, 0); PG8_LDB(B1, 0, 1); PG8_SCHED; PG8_LDA(At, 0, 0); PG8_STAGE(PG8_SA(1, 1), a1 + hstep, voffA);
;             PG8_WAIT_V(8); PG8_WAIT_L(0); PG8_BAR; PG8_MMA(0, 0, At, B0); PG8_MMA(0, 1, At, B1); PG8_BAR; PG8_SCHED;
;             PG8_LDA(At, 0, 1); PG8_STAGE(PG8_SB(0, 0), b2, voffB); PG8_STAGE(PG8_SB(0, 1), b2 + hstep, voffB); PG8_STAGE(PG8_SA(0, 0), a2, voffA);
;             PG8_WAIT_V(8); PG8_WAIT_L(0); PG8_BAR; PG8_MMA(1, 0, At, B0); PG8_MMA(1, 1, At, B1); PG8_BAR; PG8_SCHED;
.LBB0_842:
	s_add_u32 s30, s0, 0xffe00080
	s_addc_u32 s31, s1, -1
	s_add_i32 s68, 0, 0x10000
	s_cmpk_eq_i32 s67, 0x7c
	s_cselect_b32 s37, s23, s31
	s_cselect_b32 s36, s61, s30
	s_cselect_b32 s31, s19, s66
	s_cselect_b32 s30, s62, s63
	s_add_i32 s70, 0, 0x14000
	v_add_u32_e32 v142, s68, v199
	v_add_u32_e32 v162, s70, v199
	ds_read_b128 v[130:133], v142
	ds_read_b128 v[134:137], v142 offset:1024
	ds_read_b128 v[138:141], v142 offset:2048
	ds_read_b128 v[142:145], v142 offset:3072
	ds_read_b128 v[146:149], v162
	ds_read_b128 v[150:153], v162 offset:1024
	ds_read_b128 v[154:157], v162 offset:2048
	ds_read_b128 v[162:165], v162 offset:3072
	s_add_u32 s98, s0, 0xffe00000
	s_addc_u32 s99, s1, -1
	s_mov_b32 m0, s56
	s_nop 0
	global_load_lds_dwordx4 v172, s[98:99]
	s_mov_b32 m0, s57
	s_nop 0
	global_load_lds_dwordx4 v174, s[98:99]
	s_add_i32 m0, s51, 0xc000
	ds_read_b128 v[176:179], v201
	ds_read_b128 v[180:183], v201 offset:1024
	ds_read_b128 v[184:187], v201 offset:2048
	ds_read_b128 v[188:191], v201 offset:3072
	ds_read_b128 v[202:205], v201 offset:4096
	ds_read_b128 v[206:209], v201 offset:5120
	ds_read_b128 v[210:213], v201 offset:6144
	ds_read_b128 v[214:217], v201 offset:7168
	global_load_lds_dwordx4 v172, s[0:1]
	s_add_i32 m0, s51, 0xe000
	s_nop 0
	global_load_lds_dwordx4 v174, s[0:1]
	s_waitcnt vmcnt(8)
	s_waitcnt lgkmcnt(0)
	s_barrier
	s_waitcnt lgkmcnt(0)
	v_mfma_f32_16x16x32_bf16 v[126:129], v[130:133], v[176:179], v[126:129]
	v_mfma_f32_16x16x32_bf16 v[122:125], v[138:141], v[176:179], v[122:125]
	v_mfma_f32_16x16x32_bf16 v[110:113], v[130:133], v[184:187], v[110:113]
	v_mfma_f32_16x16x32_bf16 v[106:109], v[138:141], v[184:187], v[106:109]
	v_mfma_f32_16x16x32_bf16 v[94:97], v[130:133], v[202:205], v[94:97]
	v_mfma_f32_16x16x32_bf16 v[90:93], v[138:141], v[202:205], v[90:93]
	v_mfma_f32_16x16x32_bf16 v[78:81], v[130:133], v[210:213], v[78:81]
	v_mfma_f32_16x16x32_bf16 v[74:77], v[138:141], v[210:213], v[74:77]
	v_mfma_f32_16x16x32_bf16 v[126:129], v[134:137], v[180:183], v[126:129]
	v_mfma_f32_16x16x32_bf16 v[122:125], v[142:145], v[180:183], v[122:125]
	v_mfma_f32_16x16x32_bf16 v[110:113], v[134:137], v[188:191], v[110:113]
	v_mfma_f32_16x16x32_bf16 v[106:109], v[142:145], v[188:191], v[106:109]
	v_mfma_f32_16x16x32_bf16 v[94:97], v[134:137], v[206:209], v[94:97]
	v_mfma_f32_16x16x32_bf16 v[90:93], v[142:145], v[206:209], v[90:93]
	v_mfma_f32_16x16x32_bf16 v[78:81], v[134:137], v[214:217], v[78:81]
	v_mfma_f32_16x16x32_bf16 v[74:77], v[142:145], v[214:217], v[74:77]
	v_mfma_f32_16x16x32_bf16 v[118:121], v[146:149], v[176:179], v[118:121]
	v_mfma_f32_16x16x32_bf16 v[114:117], v[154:157], v[176:179], v[114:117]
	v_mfma_f32_16x16x32_bf16 v[102:105], v[146:149], v[184:187], v[102:105]
	v_mfma_f32_16x16x32_bf16 v[98:101], v[154:157], v[184:187], v[98:101]
	v_mfma_f32_16x16x32_bf16 v[86:89], v[146:149], v[202:205], v[86:89]
	v_mfma_f32_16x16x32_bf16 v[82:85], v[154:157], v[202:205], v[82:85]
	v_mfma_f32_16x16x32_bf16 v[70:73], v[146:149], v[210:213], v[70:73]
	v_mfma_f32_16x16x32_bf16 v[66:69], v[154:157], v[210:213], v[66:69]
	v_mfma_f32_16x16x32_bf16 v[118:121], v[150:153], v[180:183], v[118:121]
	v_mfma_f32_16x16x32_bf16 v[114:117], v[162:165], v[180:183], v[114:117]
	v_mfma_f32_16x16x32_bf16 v[102:105], v[150:153], v[188:191], v[102:105]
	v_mfma_f32_16x16x32_bf16 v[98:101], v[162:165], v[188:191], v[98:101]
	v_mfma_f32_16x16x32_bf16 v[86:89], v[150:153], v[206:209], v[86:89]
	v_mfma_f32_16x16x32_bf16 v[82:85], v[162:165], v[206:209], v[82:85]
	v_mfma_f32_16x16x32_bf16 v[70:73], v[150:153], v[214:217], v[70:73]
	v_mfma_f32_16x16x32_bf16 v[66:69], v[162:165], v[214:217], v[66:69]
	s_barrier
	s_add_i32 s68, s68, s50
	s_mov_b32 m0, s68
	ds_read_b128 v[176:179], v201 offset:16384
	ds_read_b128 v[180:183], v201 offset:17408
	ds_read_b128 v[184:187], v201 offset:18432
	ds_read_b128 v[188:191], v201 offset:19456
	ds_read_b128 v[202:205], v201 offset:20480
	ds_read_b128 v[206:209], v201 offset:21504
	ds_read_b128 v[210:213], v201 offset:22528
	ds_read_b128 v[214:217], v201 offset:23552
	global_load_lds_dwordx4 v158, s[30:31]
	s_add_i32 m0, s68, 0x2000
	s_add_u32 s68, s30, 0x200000
	s_addc_u32 s69, s31, 0
	s_add_i32 s70, s70, s50
	global_load_lds_dwordx4 v166, s[30:31]
	s_mov_b32 m0, s70
	s_nop 0
	global_load_lds_dwordx4 v158, s[68:69]
	s_add_i32 m0, s70, 0x2000
	s_nop 0
	global_load_lds_dwordx4 v166, s[68:69]
	s_waitcnt vmcnt(6)
	s_waitcnt lgkmcnt(0)
	s_barrier
	s_waitcnt lgkmcnt(0)
	v_mfma_f32_16x16x32_bf16 v[62:65], v[130:133], v[176:179], v[62:65]
	v_mfma_f32_16x16x32_bf16 v[58:61], v[138:141], v[176:179], v[58:61]
	v_mfma_f32_16x16x32_bf16 v[46:49], v[130:133], v[184:187], v[46:49]
	v_mfma_f32_16x16x32_bf16 v[42:45], v[138:141], v[184:187], v[42:45]
	v_mfma_f32_16x16x32_bf16 v[30:33], v[130:133], v[202:205], v[30:33]
	v_mfma_f32_16x16x32_bf16 v[26:29], v[138:141], v[202:205], v[26:29]
	v_mfma_f32_16x16x32_bf16 v[14:17], v[130:133], v[210:213], v[14:17]
	v_mfma_f32_16x16x32_bf16 v[10:13], v[138:141], v[210:213], v[10:13]
	v_mfma_f32_16x16x32_bf16 v[62:65], v[134:137], v[180:183], v[62:65]
	v_mfma_f32_16x16x32_bf16 v[58:61], v[142:145], v[180:183], v[58:61]
	v_mfma_f32_16x16x32_bf16 v[46:49], v[134:137], v[188:191], v[46:49]
	v_mfma_f32_16x16x32_bf16 v[42:45], v[142:145], v[188:191], v[42:45]
	v_mfma_f32_16x16x32_bf16 v[30:33], v[134:137], v[206:209], v[30:33]
	v_mfma_f32_16x16x32_bf16 v[26:29], v[142:145], v[206:209], v[26:29]
	v_mfma_f32_16x16x32_bf16 v[14:17], v[134:137], v[214:217], v[14:17]
	v_mfma_f32_16x16x32_bf16 v[10:13], v[142:145], v[214:217], v[10:13]
	v_mfma_f32_16x16x32_bf16 v[54:57], v[146:149], v[176:179], v[54:57]
	v_mfma_f32_16x16x32_bf16 v[50:53], v[154:157], v[176:179], v[50:53]
	v_mfma_f32_16x16x32_bf16 v[38:41], v[146:149], v[184:187], v[38:41]
	v_mfma_f32_16x16x32_bf16 v[34:37], v[154:157], v[184:187], v[34:37]
	v_mfma_f32_16x16x32_bf16 v[22:25], v[146:149], v[202:205], v[22:25]
	v_mfma_f32_16x16x32_bf16 v[18:21], v[154:157], v[202:205], v[18:21]
	v_mfma_f32_16x16x32_bf16 v[6:9], v[146:149], v[210:213], v[6:9]
	v_mfma_f32_16x16x32_bf16 v[2:5], v[154:157], v[210:213], v[2:5]
	v_mfma_f32_16x16x32_bf16 v[54:57], v[150:153], v[180:183], v[54:57]
	v_mfma_f32_16x16x32_bf16 v[50:53], v[162:165], v[180:183], v[50:53]
	v_mfma_f32_16x16x32_bf16 v[38:41], v[150:153], v[188:191], v[38:41]
	v_mfma_f32_16x16x32_bf16 v[34:37], v[162:165], v[188:191], v[34:37]
	v_mfma_f32_16x16x32_bf16 v[22:25], v[150:153], v[206:209], v[22:25]
	v_mfma_f32_16x16x32_bf16 v[18:21], v[162:165], v[206:209], v[18:21]
	v_mfma_f32_16x16x32_bf16 v[6:9], v[150:153], v[214:217], v[6:9]
	v_mfma_f32_16x16x32_bf16 v[2:5], v[162:165], v[214:217], v[2:5]
	s_barrier
; #define PG8_STAGE(bufoff, gbase, voff) do { _Pragma("unroll") for (int _i = 0; _i < 2; ++_i) \
;         __builtin_amdgcn_global_load_lds((const unsigned*)((const char*)(gbase) + (voff)[_i]), (PG8_LAS unsigned*)(lds + (bufoff) + ldsw + _i * 8192), 16, 0, 0); } while (0)
; #define PG8_LDA(dst, b, h) do { _Pragma("unroll") for (int m = 0; m < 4; ++m) _Pragma("unroll") for (int k = 0; k < 2; ++k) dst[m][k] = *(const PG8_LAS bf16x8*)(lds + PG8_SA(b, h) + aoff + m * 2048 + k * 1024); } while (0)
; #define PG8_LDB(dst, b, h) do { _Pragma("unroll") for (int n = 0; n < 2; ++n) _Pragma("unroll") for (int k = 0; k < 2; ++k) dst[n][k] = *(const PG8_LAS bf16x8*)(lds + PG8_SB(b, h) + boff + n * 2048 + k * 1024); } while (0)
; #define PG8_MMA(ai, bj, At, Bt) do { __builtin_amdgcn_s_setprio(1); _Pragma("unroll") for (int m = 0; m < 4; ++m) _Pragma("unroll") for (int n = 0; n < 2; ++n) _Pragma("unroll") for (int k = 0; k < 2; ++k) \
;         acc[ai][bj][m][n] = __builtin_amdgcn_mfma_f32_16x16x32_bf16(Bt[n][k], At[m][k], acc[ai][bj][m][n], 0, 0, 0); __builtin_amdgcn_s_setprio(0); } while (0)
; #define PG8_WAIT_V(n) asm volatile("s_waitcnt vmcnt(" #n ")" ::: "memory")
; #define PG8_WAIT_L(n) asm volatile("s_waitcnt lgkmcnt(" #n ")" ::: "memory")
; #define PG8_BAR __builtin_amdgcn_s_barrier()
; #define PG8_SCHED __builtin_amdgcn_sched_barrier(0)
; template <class Epi, class Sched, bool ALIGN_EPI = false, bool SP2 = false>
; __device__ __forceinline__ void gemm_phase(PG8_LAS unsigned char* lds, const Gemm g, const Sched& S, const Epi& E) {
;     ...
;             PG8_LDB(B0, 1, 0); PG8_LDB(B1, 1, 1); PG8_SCHED; PG8_LDA(At, 1, 0); PG8_STAGE(PG8_SA(0, 1), a2 + hstep, voffA);
;             PG8_WAIT_V(8); PG8_WAIT_L(0); PG8_BAR; PG8_MMA(0, 0, At, B0); PG8_MMA(0, 1, At, B1); PG8_BAR; PG8_SCHED;
;             PG8_LDA(At, 1, 1); PG8_STAGE(PG8_SB(1, 0), b3, voffB); PG8_STAGE(PG8_SB(1, 1), b3 + hstep, voffB); PG8_STAGE(PG8_SA(1, 0), a3, voffA);
;             PG8_WAIT_V(8); PG8_WAIT_L(0); PG8_BAR; PG8_MMA(1, 0, At, B0); PG8_MMA(1, 1, At, B1); PG8_BAR; PG8_SCHED;
;     ...
;         if constexpr (ALIGN_EPI) { if (wr == 0) PG8_BAR; }
	s_add_i32 s68, 0, 0x18000
	s_add_i32 s69, 0, 0x1c000
	v_add_u32_e32 v142, s68, v199
	v_add_u32_e32 v162, s69, v199
	ds_read_b128 v[130:133], v142
	ds_read_b128 v[134:137], v142 offset:1024
	ds_read_b128 v[138:141], v142 offset:2048
	ds_read_b128 v[142:145], v142 offset:3072
	ds_read_b128 v[146:149], v162
	ds_read_b128 v[150:153], v162 offset:1024
	ds_read_b128 v[154:157], v162 offset:2048
	ds_read_b128 v[162:165], v162 offset:3072
	s_mov_b32 m0, s51
	s_nop 0
	global_load_lds_dwordx4 v170, s[36:37]
	s_mov_b32 m0, s52
	s_nop 0
	global_load_lds_dwordx4 v168, s[36:37]
	s_add_u32 s36, s36, 0x200000
	s_addc_u32 s37, s37, 0
	s_mov_b32 m0, s53
	ds_read_b128 v[176:179], v201 offset:32768
	ds_read_b128 v[180:183], v201 offset:33792
	ds_read_b128 v[184:187], v201 offset:34816
	ds_read_b128 v[188:191], v201 offset:35840
	ds_read_b128 v[202:205], v201 offset:36864
	ds_read_b128 v[206:209], v201 offset:37888
	ds_read_b128 v[210:213], v201 offset:38912
	ds_read_b128 v[214:217], v201 offset:39936
	global_load_lds_dwordx4 v170, s[36:37]
	s_mov_b32 m0, s54
	s_nop 0
	global_load_lds_dwordx4 v168, s[36:37]
	s_waitcnt vmcnt(8)
	s_waitcnt lgkmcnt(0)
	s_barrier
	s_waitcnt lgkmcnt(0)
	v_mfma_f32_16x16x32_bf16 v[126:129], v[130:133], v[176:179], v[126:129]
	v_mfma_f32_16x16x32_bf16 v[122:125], v[138:141], v[176:179], v[122:125]
	v_mfma_f32_16x16x32_bf16 v[110:113], v[130:133], v[184:187], v[110:113]
	v_mfma_f32_16x16x32_bf16 v[106:109], v[138:141], v[184:187], v[106:109]
	v_mfma_f32_16x16x32_bf16 v[94:97], v[130:133], v[202:205], v[94:97]
	v_mfma_f32_16x16x32_bf16 v[90:93], v[138:141], v[202:205], v[90:93]
	v_mfma_f32_16x16x32_bf16 v[78:81], v[130:133], v[210:213], v[78:81]
	v_mfma_f32_16x16x32_bf16 v[74:77], v[138:141], v[210:213], v[74:77]
	v_mfma_f32_16x16x32_bf16 v[126:129], v[134:137], v[180:183], v[126:129]
	v_mfma_f32_16x16x32_bf16 v[122:125], v[142:145], v[180:183], v[122:125]
	v_mfma_f32_16x16x32_bf16 v[110:113], v[134:137], v[188:191], v[110:113]
	v_mfma_f32_16x16x32_bf16 v[106:109], v[142:145], v[188:191], v[106:109]
	v_mfma_f32_16x16x32_bf16 v[94:97], v[134:137], v[206:209], v[94:97]
	v_mfma_f32_16x16x32_bf16 v[90:93], v[142:145], v[206:209], v[90:93]
	v_mfma_f32_16x16x32_bf16 v[78:81], v[134:137], v[214:217], v[78:81]
	v_mfma_f32_16x16x32_bf16 v[74:77], v[142:145], v[214:217], v[74:77]
	v_mfma_f32_16x16x32_bf16 v[118:121], v[146:149], v[176:179], v[118:121]
	v_mfma_f32_16x16x32_bf16 v[114:117], v[154:157], v[176:179], v[114:117]
	v_mfma_f32_16x16x32_bf16 v[102:105], v[146:149], v[184:187], v[102:105]
	v_mfma_f32_16x16x32_bf16 v[98:101], v[154:157], v[184:187], v[98:101]
	v_mfma_f32_16x16x32_bf16 v[86:89], v[146:149], v[202:205], v[86:89]
	v_mfma_f32_16x16x32_bf16 v[82:85], v[154:157], v[202:205], v[82:85]
	v_mfma_f32_16x16x32_bf16 v[70:73], v[146:149], v[210:213], v[70:73]
	v_mfma_f32_16x16x32_bf16 v[66:69], v[154:157], v[210:213], v[66:69]
	v_mfma_f32_16x16x32_bf16 v[118:121], v[150:153], v[180:183], v[118:121]
	v_mfma_f32_16x16x32_bf16 v[114:117], v[162:165], v[180:183], v[114:117]
	v_mfma_f32_16x16x32_bf16 v[102:105], v[150:153], v[188:191], v[102:105]
	v_mfma_f32_16x16x32_bf16 v[98:101], v[162:165], v[188:191], v[98:101]
	v_mfma_f32_16x16x32_bf16 v[86:89], v[150:153], v[206:209], v[86:89]
	v_mfma_f32_16x16x32_bf16 v[82:85], v[162:165], v[206:209], v[82:85]
	v_mfma_f32_16x16x32_bf16 v[70:73], v[150:153], v[214:217], v[70:73]
	v_mfma_f32_16x16x32_bf16 v[66:69], v[162:165], v[214:217], v[66:69]
	s_barrier
	s_add_i32 s36, s68, s50
	s_add_i32 m0, s36, 0xffffff80
	ds_read_b128 v[176:179], v201 offset:49152
	ds_read_b128 v[180:183], v201 offset:50176
	ds_read_b128 v[184:187], v201 offset:51200
	ds_read_b128 v[188:191], v201 offset:52224
	ds_read_b128 v[202:205], v201 offset:53248
	ds_read_b128 v[206:209], v201 offset:54272
	ds_read_b128 v[210:213], v201 offset:55296
	ds_read_b128 v[214:217], v201 offset:56320
	global_load_lds_dwordx4 v158, s[30:31] offset:128
	s_add_i32 m0, s36, 0x1f80
	s_add_i32 s36, s69, s50
	global_load_lds_dwordx4 v166, s[30:31] offset:128
	s_add_u32 s30, s30, 0x200080
	s_addc_u32 s31, s31, 0
	s_mov_b32 m0, s36
	s_nop 0
	global_load_lds_dwordx4 v158, s[30:31]
	s_add_i32 m0, s36, 0x2000
	s_nop 0
	global_load_lds_dwordx4 v166, s[30:31]
	s_waitcnt vmcnt(6)
	s_waitcnt lgkmcnt(0)
	s_barrier
	s_waitcnt lgkmcnt(0)
	v_mfma_f32_16x16x32_bf16 v[62:65], v[130:133], v[176:179], v[62:65]
	v_mfma_f32_16x16x32_bf16 v[58:61], v[138:141], v[176:179], v[58:61]
	v_mfma_f32_16x16x32_bf16 v[46:49], v[130:133], v[184:187], v[46:49]
	v_mfma_f32_16x16x32_bf16 v[42:45], v[138:141], v[184:187], v[42:45]
	v_mfma_f32_16x16x32_bf16 v[30:33], v[130:133], v[202:205], v[30:33]
	v_mfma_f32_16x16x32_bf16 v[26:29], v[138:141], v[202:205], v[26:29]
	v_mfma_f32_16x16x32_bf16 v[14:17], v[130:133], v[210:213], v[14:17]
	v_mfma_f32_16x16x32_bf16 v[10:13], v[138:141], v[210:213], v[10:13]
	v_mfma_f32_16x16x32_bf16 v[62:65], v[134:137], v[180:183], v[62:65]
	v_mfma_f32_16x16x32_bf16 v[58:61], v[142:145], v[180:183], v[58:61]
	v_mfma_f32_16x16x32_bf16 v[46:49], v[134:137], v[188:191], v[46:49]
	v_mfma_f32_16x16x32_bf16 v[42:45], v[142:145], v[188:191], v[42:45]
	v_mfma_f32_16x16x32_bf16 v[30:33], v[134:137], v[206:209], v[30:33]
	v_mfma_f32_16x16x32_bf16 v[26:29], v[142:145], v[206:209], v[26:29]
	v_mfma_f32_16x16x32_bf16 v[14:17], v[134:137], v[214:217], v[14:17]
	v_mfma_f32_16x16x32_bf16 v[10:13], v[142:145], v[214:217], v[10:13]
	v_mfma_f32_16x16x32_bf16 v[54:57], v[146:149], v[176:179], v[54:57]
	v_mfma_f32_16x16x32_bf16 v[50:53], v[154:157], v[176:179], v[50:53]
	v_mfma_f32_16x16x32_bf16 v[38:41], v[146:149], v[184:187], v[38:41]
	v_mfma_f32_16x16x32_bf16 v[34:37], v[154:157], v[184:187], v[34:37]
	v_mfma_f32_16x16x32_bf16 v[22:25], v[146:149], v[202:205], v[22:25]
	v_mfma_f32_16x16x32_bf16 v[18:21], v[154:157], v[202:205], v[18:21]
	v_mfma_f32_16x16x32_bf16 v[6:9], v[146:149], v[210:213], v[6:9]
	v_mfma_f32_16x16x32_bf16 v[2:5], v[154:157], v[210:213], v[2:5]
	v_mfma_f32_16x16x32_bf16 v[54:57], v[150:153], v[180:183], v[54:57]
	v_mfma_f32_16x16x32_bf16 v[50:53], v[162:165], v[180:183], v[50:53]
	v_mfma_f32_16x16x32_bf16 v[38:41], v[150:153], v[188:191], v[38:41]
	v_mfma_f32_16x16x32_bf16 v[34:37], v[162:165], v[188:191], v[34:37]
	v_mfma_f32_16x16x32_bf16 v[22:25], v[150:153], v[206:209], v[22:25]
	v_mfma_f32_16x16x32_bf16 v[18:21], v[162:165], v[206:209], v[18:21]
	v_mfma_f32_16x16x32_bf16 v[6:9], v[150:153], v[214:217], v[6:9]
	v_mfma_f32_16x16x32_bf16 v[2:5], v[162:165], v[214:217], v[2:5]
	s_barrier
	s_add_i32 s67, s67, 2
	s_add_u32 s0, s0, 0x100
	s_addc_u32 s1, s1, 0
	s_add_u32 s63, s63, 0x100
	s_addc_u32 s66, s66, 0
	s_cmpk_gt_u32 s67, 0x7d
	s_cbranch_scc0 .LBB0_842
	s_and_b64 vcc, exec, s[16:17]
	s_cbranch_vccz .LBB0_845
	s_barrier

; #define PG8_STAGE(bufoff, gbase, voff) do { _Pragma("unroll") for (int _i = 0; _i < 2; ++_i) \
;         __builtin_amdgcn_global_load_lds((const unsigned*)((const char*)(gbase) + (voff)[_i]), (PG8_LAS unsigned*)(lds + (bufoff) + ldsw + _i * 8192), 16, 0, 0); } while (0)
; #define PG8_WAIT_V(n) asm volatile("s_waitcnt vmcnt(" #n ")" ::: "memory")
; #define PG8_BAR __builtin_amdgcn_s_barrier()
; template <class Epi, class Sched, bool ALIGN_EPI = false, bool SP2 = false>
; __device__ __forceinline__ void gemm_phase(PG8_LAS unsigned char* lds, const Gemm g, const Sched& S, const Epi& E) {
;     ...
;     for (int i = 0; i < 2; ++i) { int R, C; stage_rc(tid * 16 + i * 8192, R, C); const int Rb = Epi::PERM ? ((R & ~31) + perm32(R & 31)) : R;
;         voffA[i] = (unsigned)(R * K + C) * 2u; voffB[i] = (unsigned)(Rb * K + C) * 2u; }
;     const size_t kstep = (size_t)(BK * 2);
;     const size_t hstep = (size_t)HALF * K * 2;
;     const size_t tstep = 2 * hstep;
;     const unsigned ldsw = (unsigned)wid * 1024u;
;     const int aoff = lds_byte(wr * 64 + fr, fq * 8), boff = lds_byte(wc * 32 + fr, fq * 8);
;     ...
;         PG8_WAIT_V(2); PG8_BAR;
;         PG8_STAGE(PG8_SB(1, 0), cB + kstep, voffB); PG8_STAGE(PG8_SA(1, 0), cA + kstep, voffA); PG8_STAGE(PG8_SB(1, 1), cB + hstep + kstep, voffB);
;         PG8_WAIT_V(6); PG8_BAR;
.LBB0_870:
	v_lshrrev_b32_e32 v18, 1, v16
	v_and_b32_e32 v18, 24, v18
	s_lshl_b32 s15, s15, 5
	v_and_b32_e32 v17, 15, v16
	v_lshlrev_b32_e32 v19, 1, v18
	v_lshlrev_b32_e32 v16, 2, v16
	s_and_b32 s18, s15, 0x60
	s_add_i32 m0, s36, 0x18000
	v_lshl_add_u64 v[8:9], v[8:9], 0, s[10:11]
	v_lshl_or_b32 v161, s16, 6, v17
	v_lshl_or_b32 v17, v17, 6, v19
	s_lshl_b32 s16, s16, 13
	v_and_b32_e32 v16, 32, v16
	s_lshl_b32 s15, s18, 7
	s_waitcnt vmcnt(2)
	s_barrier
	global_load_lds_dwordx4 v[8:9], off
	v_lshl_add_u64 v[6:7], v[6:7], 0, s[10:11]
	s_add_i32 m0, s36, 0x1a000
	s_add_i32 s44, s36, 0x8000
	s_add_i32 s45, s36, 0xa000
	v_bitop3_b32 v19, v17, s16, v16 bitop3:0xde
	global_load_lds_dwordx4 v[6:7], off
	v_lshl_add_u64 v[2:3], v[2:3], 0, s[10:11]
	s_mov_b32 m0, s44
	s_add_u32 s16, s28, 0x200080
	global_load_lds_dwordx4 v[2:3], off
	v_lshl_add_u64 v[2:3], v[4:5], 0, s[10:11]
	s_mov_b32 m0, s45
	s_addc_u32 s17, s29, 0
	global_load_lds_dwordx4 v[2:3], off
	s_add_i32 m0, s36, 0x1c000
	v_lshl_add_u64 v[2:3], s[16:17], 0, v[158:159]
	global_load_lds_dwordx4 v[2:3], off
	v_lshl_add_u64 v[2:3], s[16:17], 0, v[150:151]
	s_add_i32 m0, s36, 0x1e000
	s_cmpk_lt_u32 s14, 0x100
	global_load_lds_dwordx4 v[2:3], off
	v_lshlrev_b32_e32 v2, 17, v14
	v_and_b32_e32 v2, 0xfffc0000, v2
	v_lshl_add_u32 v2, v13, 14, v2
	v_and_b32_e32 v3, 1, v14
	v_lshl_or_b32 v2, v3, 6, v2
	v_lshl_add_u32 v156, v15, 1, v2
	v_lshlrev_b32_e32 v2, 17, v10
	v_and_b32_e32 v2, 0xfffc0000, v2
	s_waitcnt vmcnt(6)
	v_lshl_add_u32 v2, v11, 14, v2
	v_and_b32_e32 v3, 1, v10
	v_lshl_or_b32 v2, v3, 6, v2
	v_readlane_b32 s16, v252, 22
	v_bitop3_b32 v178, v17, s15, v16 bitop3:0xde
	s_cselect_b64 s[14:15], -1, 0
	s_cbranch_scc1 .Lsp_5
	s_setprio 1
.Lsp_5:
	s_ashr_i32 s50, s21, 31
	v_or_b32_e32 v179, s18, v18
	v_mov_b32_e32 v157, v159
	v_lshl_add_u32 v166, v12, 1, v2
	v_mov_b32_e32 v167, v159
	s_mov_b32 s51, 0
	v_add_u32_e32 v180, 0, v19
	v_readlane_b32 s52, v254, 48
	s_mov_b32 s53, s16
	s_barrier
	v_readlane_b32 s17, v252, 23
	s_branch .LBB0_873

; #define PG8_STAGE(bufoff, gbase, voff) do { _Pragma("unroll") for (int _i = 0; _i < 2; ++_i) \
;         __builtin_amdgcn_global_load_lds((const unsigned*)((const char*)(gbase) + (voff)[_i]), (PG8_LAS unsigned*)(lds + (bufoff) + ldsw + _i * 8192), 16, 0, 0); } while (0)
; #define PG8_LDA(dst, b, h) do { _Pragma("unroll") for (int m = 0; m < 4; ++m) _Pragma("unroll") for (int k = 0; k < 2; ++k) dst[m][k] = *(const PG8_LAS bf16x8*)(lds + PG8_SA(b, h) + aoff + m * 2048 + k * 1024); } while (0)
; #define PG8_LDB(dst, b, h) do { _Pragma("unroll") for (int n = 0; n < 2; ++n) _Pragma("unroll") for (int k = 0; k < 2; ++k) dst[n][k] = *(const PG8_LAS bf16x8*)(lds + PG8_SB(b, h) + boff + n * 2048 + k * 1024); } while (0)
; #define PG8_MMA(ai, bj, At, Bt) do { __builtin_amdgcn_s_setprio(1); _Pragma("unroll") for (int m = 0; m < 4; ++m) _Pragma("unroll") for (int n = 0; n < 2; ++n) _Pragma("unroll") for (int k = 0; k < 2; ++k) \
;         acc[ai][bj][m][n] = __builtin_amdgcn_mfma_f32_16x16x32_bf16(Bt[n][k], At[m][k], acc[ai][bj][m][n], 0, 0, 0); __builtin_amdgcn_s_setprio(0); } while (0)
; #define PG8_WAIT_V(n) asm volatile("s_waitcnt vmcnt(" #n ")" ::: "memory")
; #define PG8_BAR __builtin_amdgcn_s_barrier()
; template <class Epi, class Sched, bool ALIGN_EPI = false, bool SP2 = false>
; __device__ __forceinline__ void gemm_phase(PG8_LAS unsigned char* lds, const Gemm g, const Sched& S, const Epi& E) {
;     ...
;         for (int t = 0; t < nt; t += 2) {
;             const bool last = (t == nt - 2);
;             const char* a1 = cA + (size_t)(t + 1) * kstep;
;             const char* a2 = last ? nA : cA + (size_t)(t + 2) * kstep; const char* b2 = last ? nB : cB + (size_t)(t + 2) * kstep;
;             const char* a3 = a2 + kstep; const char* b3 = b2 + kstep;
;             if (last && has_next) S.a_ready(nxt);
;             if constexpr (SP2) {
;             PG8_LDB(B0, 0, 0); PG8_LDB(B1, 0, 1); PG8_SCHED; PG8_LDA(At, 0, 0); PG8_STAGE(PG8_SA(1, 1), a1 + hstep, voffA);
;             PG8_WAIT_V(8); PG8_WAIT_L(0); PG8_BAR; PG8_MMA(0, 0, At, B0); PG8_MMA(0, 1, At, B1); PG8_BAR; PG8_SCHED;
;             PG8_LDA(At, 0, 1); PG8_STAGE(PG8_SB(0, 0), b2, voffB); PG8_STAGE(PG8_SB(0, 1), b2 + hstep, voffB); PG8_STAGE(PG8_SA(0, 0), a2, voffA);
;             PG8_WAIT_V(8); PG8_WAIT_L(0); PG8_BAR; PG8_MMA(1, 0, At, B0); PG8_MMA(1, 1, At, B1); PG8_BAR; PG8_SCHED;
.LBB0_880:
	s_add_u32 s28, s0, 0xffe00080
	s_addc_u32 s29, s1, -1
	s_add_i32 s59, 0, 0x10000
	s_cmpk_eq_i32 s58, 0x7c
	s_cselect_b32 s31, s19, s29
	s_cselect_b32 s30, s54, s28
	s_cselect_b32 s29, s17, s57
	s_cselect_b32 s28, s55, s56
	s_add_i32 s62, 0, 0x14000
	v_add_u32_e32 v142, s59, v178
	v_add_u32_e32 v172, s62, v178
	ds_read_b128 v[130:133], v142
	ds_read_b128 v[134:137], v142 offset:1024
	ds_read_b128 v[138:141], v142 offset:2048
	ds_read_b128 v[142:145], v142 offset:3072
	ds_read_b128 v[146:149], v172
	ds_read_b128 v[162:165], v172 offset:1024
	ds_read_b128 v[168:171], v172 offset:2048
	ds_read_b128 v[172:175], v172 offset:3072
	s_add_u32 s98, s0, 0xffe00000
	s_addc_u32 s99, s1, -1
	s_mov_b32 m0, s44
	s_nop 0
	global_load_lds_dwordx4 v156, s[98:99]
	s_mov_b32 m0, s45
	s_nop 0
	global_load_lds_dwordx4 v166, s[98:99]
	s_add_i32 m0, s36, 0xc000
	ds_read_b128 v[182:185], v180
	ds_read_b128 v[186:189], v180 offset:1024
	ds_read_b128 v[190:193], v180 offset:2048
	ds_read_b128 v[200:203], v180 offset:3072
	ds_read_b128 v[204:207], v180 offset:4096
	ds_read_b128 v[208:211], v180 offset:5120
	ds_read_b128 v[212:215], v180 offset:6144
	ds_read_b128 v[216:219], v180 offset:7168
	global_load_lds_dwordx4 v156, s[0:1]
	s_add_i32 m0, s36, 0xe000
	s_nop 0
	global_load_lds_dwordx4 v166, s[0:1]
	s_waitcnt vmcnt(8)
	s_waitcnt lgkmcnt(0)
	s_barrier
	s_waitcnt lgkmcnt(0)
	v_mfma_f32_16x16x32_bf16 v[126:129], v[130:133], v[182:185], v[126:129]
	v_mfma_f32_16x16x32_bf16 v[122:125], v[138:141], v[182:185], v[122:125]
	v_mfma_f32_16x16x32_bf16 v[118:121], v[130:133], v[190:193], v[118:121]
	v_mfma_f32_16x16x32_bf16 v[114:117], v[138:141], v[190:193], v[114:117]
	v_mfma_f32_16x16x32_bf16 v[94:97], v[130:133], v[204:207], v[94:97]
	v_mfma_f32_16x16x32_bf16 v[90:93], v[138:141], v[204:207], v[90:93]
	v_mfma_f32_16x16x32_bf16 v[82:85], v[130:133], v[212:215], v[82:85]
	v_mfma_f32_16x16x32_bf16 v[74:77], v[138:141], v[212:215], v[74:77]
	v_mfma_f32_16x16x32_bf16 v[126:129], v[134:137], v[186:189], v[126:129]
	v_mfma_f32_16x16x32_bf16 v[122:125], v[142:145], v[186:189], v[122:125]
	v_mfma_f32_16x16x32_bf16 v[118:121], v[134:137], v[200:203], v[118:121]
	v_mfma_f32_16x16x32_bf16 v[114:117], v[142:145], v[200:203], v[114:117]
	v_mfma_f32_16x16x32_bf16 v[94:97], v[134:137], v[208:211], v[94:97]
	v_mfma_f32_16x16x32_bf16 v[90:93], v[142:145], v[208:211], v[90:93]
	v_mfma_f32_16x16x32_bf16 v[82:85], v[134:137], v[216:219], v[82:85]
	v_mfma_f32_16x16x32_bf16 v[74:77], v[142:145], v[216:219], v[74:77]
	v_mfma_f32_16x16x32_bf16 v[110:113], v[146:149], v[182:185], v[110:113]
	v_mfma_f32_16x16x32_bf16 v[106:109], v[168:171], v[182:185], v[106:109]
	v_mfma_f32_16x16x32_bf16 v[102:105], v[146:149], v[190:193], v[102:105]
	v_mfma_f32_16x16x32_bf16 v[98:101], v[168:171], v[190:193], v[98:101]
	v_mfma_f32_16x16x32_bf16 v[86:89], v[146:149], v[204:207], v[86:89]
	v_mfma_f32_16x16x32_bf16 v[78:81], v[168:171], v[204:207], v[78:81]
	v_mfma_f32_16x16x32_bf16 v[70:73], v[146:149], v[212:215], v[70:73]
	v_mfma_f32_16x16x32_bf16 v[66:69], v[168:171], v[212:215], v[66:69]
	v_mfma_f32_16x16x32_bf16 v[110:113], v[162:165], v[186:189], v[110:113]
	v_mfma_f32_16x16x32_bf16 v[106:109], v[172:175], v[186:189], v[106:109]
	v_mfma_f32_16x16x32_bf16 v[102:105], v[162:165], v[200:203], v[102:105]
	v_mfma_f32_16x16x32_bf16 v[98:101], v[172:175], v[200:203], v[98:101]
	v_mfma_f32_16x16x32_bf16 v[86:89], v[162:165], v[208:211], v[86:89]
	v_mfma_f32_16x16x32_bf16 v[78:81], v[172:175], v[208:211], v[78:81]
	v_mfma_f32_16x16x32_bf16 v[70:73], v[162:165], v[216:219], v[70:73]
	v_mfma_f32_16x16x32_bf16 v[66:69], v[172:175], v[216:219], v[66:69]
	s_barrier
	s_add_i32 s59, s59, s34
	s_mov_b32 m0, s59
	ds_read_b128 v[182:185], v180 offset:16384
	ds_read_b128 v[186:189], v180 offset:17408
	ds_read_b128 v[190:193], v180 offset:18432
	ds_read_b128 v[200:203], v180 offset:19456
	ds_read_b128 v[204:207], v180 offset:20480
	ds_read_b128 v[208:211], v180 offset:21504
	ds_read_b128 v[212:215], v180 offset:22528
	ds_read_b128 v[216:219], v180 offset:23552
	global_load_lds_dwordx4 v158, s[28:29]
	s_add_i32 m0, s59, 0x2000
	s_add_u32 s60, s28, 0x200000
	s_addc_u32 s61, s29, 0
	s_add_i32 s59, s62, s34
	global_load_lds_dwordx4 v150, s[28:29]
	s_mov_b32 m0, s59
	s_nop 0
	global_load_lds_dwordx4 v158, s[60:61]
	s_add_i32 m0, s59, 0x2000
	s_nop 0
	global_load_lds_dwordx4 v150, s[60:61]
	s_waitcnt vmcnt(6)
	s_waitcnt lgkmcnt(0)
	s_barrier
	s_waitcnt lgkmcnt(0)
	v_mfma_f32_16x16x32_bf16 v[62:65], v[130:133], v[182:185], v[62:65]
	v_mfma_f32_16x16x32_bf16 v[58:61], v[138:141], v[182:185], v[58:61]
	v_mfma_f32_16x16x32_bf16 v[50:53], v[130:133], v[190:193], v[50:53]
	v_mfma_f32_16x16x32_bf16 v[42:45], v[138:141], v[190:193], v[42:45]
	v_mfma_f32_16x16x32_bf16 v[34:37], v[130:133], v[204:207], v[34:37]
	v_mfma_f32_16x16x32_bf16 v[26:29], v[138:141], v[204:207], v[26:29]
	v_mfma_f32_16x16x32_bf16 v[18:21], v[130:133], v[212:215], v[18:21]
	v_mfma_f32_16x16x32_bf16 v[10:13], v[138:141], v[212:215], v[10:13]
	v_mfma_f32_16x16x32_bf16 v[62:65], v[134:137], v[186:189], v[62:65]
	v_mfma_f32_16x16x32_bf16 v[58:61], v[142:145], v[186:189], v[58:61]
	v_mfma_f32_16x16x32_bf16 v[50:53], v[134:137], v[200:203], v[50:53]
	v_mfma_f32_16x16x32_bf16 v[42:45], v[142:145], v[200:203], v[42:45]
	v_mfma_f32_16x16x32_bf16 v[34:37], v[134:137], v[208:211], v[34:37]
	v_mfma_f32_16x16x32_bf16 v[26:29], v[142:145], v[208:211], v[26:29]
	v_mfma_f32_16x16x32_bf16 v[18:21], v[134:137], v[216:219], v[18:21]
	v_mfma_f32_16x16x32_bf16 v[10:13], v[142:145], v[216:219], v[10:13]
	v_mfma_f32_16x16x32_bf16 v[54:57], v[146:149], v[182:185], v[54:57]
	v_mfma_f32_16x16x32_bf16 v[46:49], v[168:171], v[182:185], v[46:49]
	v_mfma_f32_16x16x32_bf16 v[38:41], v[146:149], v[190:193], v[38:41]
	v_mfma_f32_16x16x32_bf16 v[30:33], v[168:171], v[190:193], v[30:33]
	v_mfma_f32_16x16x32_bf16 v[22:25], v[146:149], v[204:207], v[22:25]
	v_mfma_f32_16x16x32_bf16 v[14:17], v[168:171], v[204:207], v[14:17]
	v_mfma_f32_16x16x32_bf16 v[6:9], v[146:149], v[212:215], v[6:9]
	v_mfma_f32_16x16x32_bf16 v[2:5], v[168:171], v[212:215], v[2:5]
	v_mfma_f32_16x16x32_bf16 v[54:57], v[162:165], v[186:189], v[54:57]
	v_mfma_f32_16x16x32_bf16 v[46:49], v[172:175], v[186:189], v[46:49]
	v_mfma_f32_16x16x32_bf16 v[38:41], v[162:165], v[200:203], v[38:41]
	v_mfma_f32_16x16x32_bf16 v[30:33], v[172:175], v[200:203], v[30:33]
	v_mfma_f32_16x16x32_bf16 v[22:25], v[162:165], v[208:211], v[22:25]
	v_mfma_f32_16x16x32_bf16 v[14:17], v[172:175], v[208:211], v[14:17]
	v_mfma_f32_16x16x32_bf16 v[6:9], v[162:165], v[216:219], v[6:9]
	v_mfma_f32_16x16x32_bf16 v[2:5], v[172:175], v[216:219], v[2:5]
	s_barrier
; #define PG8_STAGE(bufoff, gbase, voff) do { _Pragma("unroll") for (int _i = 0; _i < 2; ++_i) \
;         __builtin_amdgcn_global_load_lds((const unsigned*)((const char*)(gbase) + (voff)[_i]), (PG8_LAS unsigned*)(lds + (bufoff) + ldsw + _i * 8192), 16, 0, 0); } while (0)
; #define PG8_LDA(dst, b, h) do { _Pragma("unroll") for (int m = 0; m < 4; ++m) _Pragma("unroll") for (int k = 0; k < 2; ++k) dst[m][k] = *(const PG8_LAS bf16x8*)(lds + PG8_SA(b, h) + aoff + m * 2048 + k * 1024); } while (0)
; #define PG8_LDB(dst, b, h) do { _Pragma("unroll") for (int n = 0; n < 2; ++n) _Pragma("unroll") for (int k = 0; k < 2; ++k) dst[n][k] = *(const PG8_LAS bf16x8*)(lds + PG8_SB(b, h) + boff + n * 2048 + k * 1024); } while (0)
; #define PG8_MMA(ai, bj, At, Bt) do { __builtin_amdgcn_s_setprio(1); _Pragma("unroll") for (int m = 0; m < 4; ++m) _Pragma("unroll") for (int n = 0; n < 2; ++n) _Pragma("unroll") for (int k = 0; k < 2; ++k) \
;         acc[ai][bj][m][n] = __builtin_amdgcn_mfma_f32_16x16x32_bf16(Bt[n][k], At[m][k], acc[ai][bj][m][n], 0, 0, 0); __builtin_amdgcn_s_setprio(0); } while (0)
; #define PG8_WAIT_V(n) asm volatile("s_waitcnt vmcnt(" #n ")" ::: "memory")
; #define PG8_WAIT_L(n) asm volatile("s_waitcnt lgkmcnt(" #n ")" ::: "memory")
; #define PG8_BAR __builtin_amdgcn_s_barrier()
; #define PG8_SCHED __builtin_amdgcn_sched_barrier(0)
; template <class Epi, class Sched, bool ALIGN_EPI = false, bool SP2 = false>
; __device__ __forceinline__ void gemm_phase(PG8_LAS unsigned char* lds, const Gemm g, const Sched& S, const Epi& E) {
;     ...
;             PG8_LDB(B0, 1, 0); PG8_LDB(B1, 1, 1); PG8_SCHED; PG8_LDA(At, 1, 0); PG8_STAGE(PG8_SA(0, 1), a2 + hstep, voffA);
;             PG8_WAIT_V(8); PG8_WAIT_L(0); PG8_BAR; PG8_MMA(0, 0, At, B0); PG8_MMA(0, 1, At, B1); PG8_BAR; PG8_SCHED;
;             PG8_LDA(At, 1, 1); PG8_STAGE(PG8_SB(1, 0), b3, voffB); PG8_STAGE(PG8_SB(1, 1), b3 + hstep, voffB); PG8_STAGE(PG8_SA(1, 0), a3, voffA);
;             PG8_WAIT_V(8); PG8_WAIT_L(0); PG8_BAR; PG8_MMA(1, 0, At, B0); PG8_MMA(1, 1, At, B1); PG8_BAR; PG8_SCHED;
;     ...
;         if constexpr (ALIGN_EPI) { if (wr == 0) PG8_BAR; }
	s_add_i32 s59, 0, 0x18000
	s_add_i32 s60, 0, 0x1c000
	v_add_u32_e32 v142, s59, v178
	v_add_u32_e32 v172, s60, v178
	ds_read_b128 v[130:133], v142
	ds_read_b128 v[134:137], v142 offset:1024
	ds_read_b128 v[138:141], v142 offset:2048
	ds_read_b128 v[142:145], v142 offset:3072
	ds_read_b128 v[146:149], v172
	ds_read_b128 v[162:165], v172 offset:1024
	ds_read_b128 v[168:171], v172 offset:2048
	ds_read_b128 v[172:175], v172 offset:3072
	s_mov_b32 m0, s36
	s_nop 0
	global_load_lds_dwordx4 v154, s[30:31]
	s_mov_b32 m0, s37
	s_nop 0
	global_load_lds_dwordx4 v152, s[30:31]
	s_add_u32 s30, s30, 0x200000
	s_addc_u32 s31, s31, 0
	s_mov_b32 m0, s42
	ds_read_b128 v[182:185], v180 offset:32768
	ds_read_b128 v[186:189], v180 offset:33792
	ds_read_b128 v[190:193], v180 offset:34816
	ds_read_b128 v[200:203], v180 offset:35840
	ds_read_b128 v[204:207], v180 offset:36864
	ds_read_b128 v[208:211], v180 offset:37888
	ds_read_b128 v[212:215], v180 offset:38912
	ds_read_b128 v[216:219], v180 offset:39936
	global_load_lds_dwordx4 v154, s[30:31]
	s_mov_b32 m0, s43
	s_nop 0
	global_load_lds_dwordx4 v152, s[30:31]
	s_waitcnt vmcnt(8)
	s_waitcnt lgkmcnt(0)
	s_barrier
	s_waitcnt lgkmcnt(0)
	v_mfma_f32_16x16x32_bf16 v[126:129], v[130:133], v[182:185], v[126:129]
	v_mfma_f32_16x16x32_bf16 v[122:125], v[138:141], v[182:185], v[122:125]
	v_mfma_f32_16x16x32_bf16 v[118:121], v[130:133], v[190:193], v[118:121]
	v_mfma_f32_16x16x32_bf16 v[114:117], v[138:141], v[190:193], v[114:117]
	v_mfma_f32_16x16x32_bf16 v[94:97], v[130:133], v[204:207], v[94:97]
	v_mfma_f32_16x16x32_bf16 v[90:93], v[138:141], v[204:207], v[90:93]
	v_mfma_f32_16x16x32_bf16 v[82:85], v[130:133], v[212:215], v[82:85]
	v_mfma_f32_16x16x32_bf16 v[74:77], v[138:141], v[212:215], v[74:77]
	v_mfma_f32_16x16x32_bf16 v[126:129], v[134:137], v[186:189], v[126:129]
	v_mfma_f32_16x16x32_bf16 v[122:125], v[142:145], v[186:189], v[122:125]
	v_mfma_f32_16x16x32_bf16 v[118:121], v[134:137], v[200:203], v[118:121]
	v_mfma_f32_16x16x32_bf16 v[114:117], v[142:145], v[200:203], v[114:117]
	v_mfma_f32_16x16x32_bf16 v[94:97], v[134:137], v[208:211], v[94:97]
	v_mfma_f32_16x16x32_bf16 v[90:93], v[142:145], v[208:211], v[90:93]
	v_mfma_f32_16x16x32_bf16 v[82:85], v[134:137], v[216:219], v[82:85]
	v_mfma_f32_16x16x32_bf16 v[74:77], v[142:145], v[216:219], v[74:77]
	v_mfma_f32_16x16x32_bf16 v[110:113], v[146:149], v[182:185], v[110:113]
	v_mfma_f32_16x16x32_bf16 v[106:109], v[168:171], v[182:185], v[106:109]
	v_mfma_f32_16x16x32_bf16 v[102:105], v[146:149], v[190:193], v[102:105]
	v_mfma_f32_16x16x32_bf16 v[98:101], v[168:171], v[190:193], v[98:101]
	v_mfma_f32_16x16x32_bf16 v[86:89], v[146:149], v[204:207], v[86:89]
	v_mfma_f32_16x16x32_bf16 v[78:81], v[168:171], v[204:207], v[78:81]
	v_mfma_f32_16x16x32_bf16 v[70:73], v[146:149], v[212:215], v[70:73]
	v_mfma_f32_16x16x32_bf16 v[66:69], v[168:171], v[212:215], v[66:69]
	v_mfma_f32_16x16x32_bf16 v[110:113], v[162:165], v[186:189], v[110:113]
	v_mfma_f32_16x16x32_bf16 v[106:109], v[172:175], v[186:189], v[106:109]
	v_mfma_f32_16x16x32_bf16 v[102:105], v[162:165], v[200:203], v[102:105]
	v_mfma_f32_16x16x32_bf16 v[98:101], v[172:175], v[200:203], v[98:101]
	v_mfma_f32_16x16x32_bf16 v[86:89], v[162:165], v[208:211], v[86:89]
	v_mfma_f32_16x16x32_bf16 v[78:81], v[172:175], v[208:211], v[78:81]
	v_mfma_f32_16x16x32_bf16 v[70:73], v[162:165], v[216:219], v[70:73]
	v_mfma_f32_16x16x32_bf16 v[66:69], v[172:175], v[216:219], v[66:69]
	s_barrier
	s_add_i32 s30, s59, s34
	s_add_i32 m0, s30, 0xffffff80
	ds_read_b128 v[182:185], v180 offset:49152
	ds_read_b128 v[186:189], v180 offset:50176
	ds_read_b128 v[190:193], v180 offset:51200
	ds_read_b128 v[200:203], v180 offset:52224
	ds_read_b128 v[204:207], v180 offset:53248
	ds_read_b128 v[208:211], v180 offset:54272
	ds_read_b128 v[212:215], v180 offset:55296
	ds_read_b128 v[216:219], v180 offset:56320
	global_load_lds_dwordx4 v158, s[28:29] offset:128
	s_add_i32 m0, s30, 0x1f80
	s_add_i32 s30, s60, s34
	global_load_lds_dwordx4 v150, s[28:29] offset:128
	s_add_u32 s28, s28, 0x200080
	s_addc_u32 s29, s29, 0
	s_mov_b32 m0, s30
	s_nop 0
	global_load_lds_dwordx4 v158, s[28:29]
	s_add_i32 m0, s30, 0x2000
	s_nop 0
	global_load_lds_dwordx4 v150, s[28:29]
	s_waitcnt vmcnt(6)
	s_waitcnt lgkmcnt(0)
	s_barrier
	s_waitcnt lgkmcnt(0)
	v_mfma_f32_16x16x32_bf16 v[62:65], v[130:133], v[182:185], v[62:65]
	v_mfma_f32_16x16x32_bf16 v[58:61], v[138:141], v[182:185], v[58:61]
	v_mfma_f32_16x16x32_bf16 v[50:53], v[130:133], v[190:193], v[50:53]
	v_mfma_f32_16x16x32_bf16 v[42:45], v[138:141], v[190:193], v[42:45]
	v_mfma_f32_16x16x32_bf16 v[34:37], v[130:133], v[204:207], v[34:37]
	v_mfma_f32_16x16x32_bf16 v[26:29], v[138:141], v[204:207], v[26:29]
	v_mfma_f32_16x16x32_bf16 v[18:21], v[130:133], v[212:215], v[18:21]
	v_mfma_f32_16x16x32_bf16 v[10:13], v[138:141], v[212:215], v[10:13]
	v_mfma_f32_16x16x32_bf16 v[62:65], v[134:137], v[186:189], v[62:65]
	v_mfma_f32_16x16x32_bf16 v[58:61], v[142:145], v[186:189], v[58:61]
	v_mfma_f32_16x16x32_bf16 v[50:53], v[134:137], v[200:203], v[50:53]
	v_mfma_f32_16x16x32_bf16 v[42:45], v[142:145], v[200:203], v[42:45]
	v_mfma_f32_16x16x32_bf16 v[34:37], v[134:137], v[208:211], v[34:37]
	v_mfma_f32_16x16x32_bf16 v[26:29], v[142:145], v[208:211], v[26:29]
	v_mfma_f32_16x16x32_bf16 v[18:21], v[134:137], v[216:219], v[18:21]
	v_mfma_f32_16x16x32_bf16 v[10:13], v[142:145], v[216:219], v[10:13]
	v_mfma_f32_16x16x32_bf16 v[54:57], v[146:149], v[182:185], v[54:57]
	v_mfma_f32_16x16x32_bf16 v[46:49], v[168:171], v[182:185], v[46:49]
	v_mfma_f32_16x16x32_bf16 v[38:41], v[146:149], v[190:193], v[38:41]
	v_mfma_f32_16x16x32_bf16 v[30:33], v[168:171], v[190:193], v[30:33]
	v_mfma_f32_16x16x32_bf16 v[22:25], v[146:149], v[204:207], v[22:25]
	v_mfma_f32_16x16x32_bf16 v[14:17], v[168:171], v[204:207], v[14:17]
	v_mfma_f32_16x16x32_bf16 v[6:9], v[146:149], v[212:215], v[6:9]
	v_mfma_f32_16x16x32_bf16 v[2:5], v[168:171], v[212:215], v[2:5]
	v_mfma_f32_16x16x32_bf16 v[54:57], v[162:165], v[186:189], v[54:57]
	v_mfma_f32_16x16x32_bf16 v[46:49], v[172:175], v[186:189], v[46:49]
	v_mfma_f32_16x16x32_bf16 v[38:41], v[162:165], v[200:203], v[38:41]
	v_mfma_f32_16x16x32_bf16 v[30:33], v[172:175], v[200:203], v[30:33]
	v_mfma_f32_16x16x32_bf16 v[22:25], v[162:165], v[208:211], v[22:25]
	v_mfma_f32_16x16x32_bf16 v[14:17], v[172:175], v[208:211], v[14:17]
	v_mfma_f32_16x16x32_bf16 v[6:9], v[162:165], v[216:219], v[6:9]
	v_mfma_f32_16x16x32_bf16 v[2:5], v[172:175], v[216:219], v[2:5]
	s_barrier
	s_add_i32 s58, s58, 2
	s_add_u32 s0, s0, 0x100
	s_addc_u32 s1, s1, 0
	s_add_u32 s56, s56, 0x100
	s_addc_u32 s57, s57, 0
	s_cmpk_gt_u32 s58, 0x7d
	s_cbranch_scc0 .LBB0_880
	s_and_b64 vcc, exec, s[14:15]
	s_cbranch_vccz .LBB0_883
	s_barrier

; __device__ __forceinline__ unsigned xb_ld(unsigned* p)              { return __hip_atomic_load(p, __ATOMIC_RELAXED, __HIP_MEMORY_SCOPE_AGENT); }
; __device__ __forceinline__ void xcd_barrier_complete(unsigned* bar, unsigned x, unsigned& nloc, unsigned& nx) {
;     const unsigned G = gridDim.x * gridDim.y * gridDim.z;
;     unsigned sum, cnt, mine, sp = 0u;
;     for (;;) {
;         sum = 0u; cnt = 0u; mine = 0u;
; #pragma unroll
;         for (unsigned j = 0; j < 16; ++j) { const unsigned c = xb_ld(&bar[XB_XCNT(j)]); sum += c; cnt += (c > 0u) ? 1u : 0u; mine = (j == x) ? c : mine; }
; __device__ __forceinline__ void xcd_barrier(const XcdBarrier& b) {
;     asm volatile("s_waitcnt vmcnt(0)" ::: "memory");
;     __syncthreads();
;     if (threadIdx.x == 0) {
;         unsigned* bar = b.bar;
;         __builtin_amdgcn_s_waitcnt(0);
;         unsigned nloc = b.st[0], nx = b.st[1];
;         if (nloc == 0u) { xcd_barrier_complete(bar, b.x, nloc, nx); b.st[0] = nloc; b.st[1] = nx; }
.LBB0_887:
	v_readlane_b32 s0, v252, 30
	v_readlane_b32 s12, v253, 2
	s_add_i32 s0, s0, 8
	v_readlane_b32 s15, v253, 5
	s_cmp_ge_i32 s0, s15
	v_readlane_b32 s13, v253, 3
	v_readlane_b32 s14, v253, 4
	s_cbranch_scc1 .LBB0_124
	s_waitcnt vmcnt(0)
	s_waitcnt vmcnt(0) lgkmcnt(0)
	s_barrier
	s_setprio 0
	s_and_saveexec_b64 s[0:1], s[80:81]
	s_cbranch_execz .LBB0_123
	v_readlane_b32 s4, v254, 61
	s_waitcnt vmcnt(0) expcnt(0) lgkmcnt(0)
	s_nop 0
	v_mov_b32_e32 v2, s4
	ds_read_b32 v4, v2
	v_readlane_b32 s4, v254, 62
	s_waitcnt lgkmcnt(0)
	v_cmp_ne_u32_e32 vcc, 0, v4
	v_mov_b32_e32 v2, s4
	ds_read_b32 v2, v2
	s_cbranch_vccnz .LBB0_904
	v_readlane_b32 s12, v253, 6
	v_readlane_b32 s13, v253, 7
	s_load_dwordx2 s[4:5], s[12:13], 0x0
	s_nop 0
	s_load_dword s12, s[12:13], 0x8
	s_mov_b32 s17, 1
	s_waitcnt lgkmcnt(0)
	s_mul_i32 s16, s5, s4
	s_mul_i32 s16, s16, s12
	s_branch .LBB0_892
